# attention: next tile's first K-fragment ds_reads hoisted above the softmax scale/exp VALU block (after barrier B1)
# baseline (speedup 1.0000x reference)
; __device__ __forceinline__ int opaque_tid() { int t = threadIdx.x; asm volatile("" : "+v"(t)); return t; }
; __device__ __forceinline__ void attn_body(const bf16_t* Qb, const bf16_t* Kh, const bf16_t* Vh, const bf16_t* Gb, bf16_t* Ob, int seq, char* lds,
;                                           const float* qgain, const float* cosA, const float* sinA, int t0) {
;   const int tid = opaque_tid(), wid = tid >> 6, lane = tid & 63, r32 = lane & 31, hi = lane >> 5;
;   char* V_lds = lds; char* K_lds = lds + 2 * SHM_V;
;   float* ws = (float*)(lds + 2 * SHM_V + 2 * SHM_K) + wid * 64; float* li_l = ws; float* al_l = ws + 32;
;   float m_reg = -1e30f, l_reg = 0; f32x16 o[4] = {}; bf16x8 qr[8];
;   const bf16_t* Qw = Qb + (long)(wid * QBLK + r32) * LDQ + hi * 8;
; #pragma unroll
;   for (int d0 = 0; d0 < 8; ++d0) qr[d0] = ld8(Qw + d0 * 16);
;   {
;     float ss = 0.f;
; #pragma unroll
;     for (int d0 = 0; d0 < 8; ++d0)
; #pragma unroll
;       for (int e = 0; e < 8; ++e) { const float v = bf2f((unsigned short)qr[d0][e]); ss += v * v; }
.LBB0_258:
	s_lshl_b32 s14, s46, 6
	s_and_b32 s20, s14, 0x300
	s_lshl_b32 s14, s48, 4
	s_and_b32 s38, s47, 0xfffff000
	s_and_b32 s15, s14, 0xfffff000
	s_ashr_i32 s39, s38, 31
	s_mul_i32 s16, s15, 0x2800
	s_mul_hi_i32 s14, s15, 0x2800
	s_add_u32 s19, s4, s16
	s_addc_u32 s21, s5, s14
	s_lshl_b32 s14, s48, 5
	s_and_b32 s17, s14, 0xf00
	s_mul_i32 s14, s17, 0x2800
	s_add_u32 s16, s19, s14
	s_addc_u32 s14, s21, 0
	s_lshl_b32 s18, s48, 8
	s_and_b32 s18, s18, 0x700
	s_and_b32 s22, s48, 0x80
	s_or_b32 s18, s18, s22
	s_lshl_b32 s22, s18, 1
	v_mov_b32_e32 v94, v252
	s_add_u32 s22, s16, s22
	s_addc_u32 s23, s14, 0
	v_ashrrev_i32_e32 v179, 6, v94
	v_and_b32_e32 v181, 31, v94
	v_lshlrev_b32_e32 v178, 5, v179
	v_bfe_u32 v184, v94, 5, 1
	v_or_b32_e32 v95, v178, v181
	v_mov_b64_e32 v[0:1], s[22:23]
	v_mad_i64_i32 v[0:1], s[22:23], v95, s72, v[0:1]
	v_lshlrev_b32_e32 v176, 4, v184
	v_lshl_add_u64 v[4:5], v[0:1], 0, v[176:177]
	s_waitcnt vmcnt(4)
	v_and_b32_e32 v38, 32, v94
	global_load_dwordx4 v[46:49], v[4:5], off offset:224
	global_load_dwordx4 v[54:57], v[4:5], off offset:160
	global_load_dwordx4 v[62:65], v[4:5], off offset:192
	global_load_dwordx4 v[66:69], v[4:5], off offset:128
	global_load_dwordx4 v[8:11], v38, s[40:41] offset:16
	global_load_dwordx4 v[0:3], v38, s[40:41] offset:144
	global_load_dwordx4 v[96:99], v[4:5], off offset:64
	global_load_dwordx4 v[80:83], v[4:5], off offset:96
	global_load_dwordx4 v[100:103], v[4:5], off
	global_load_dwordx4 v[104:107], v[4:5], off offset:32
	v_or_b32_e32 v6, s17, v181
	v_add_u32_e32 v6, v6, v178
	v_ashrrev_i32_e32 v6, 1, v6
	v_and_b32_e32 v6, 0xffffffe0, v6
	v_ashrrev_i32_e32 v7, 31, v6
	v_lshlrev_b64 v[4:5], 2, v[6:7]
	v_mov_b32_e32 v39, v177
	v_lshl_add_u64 v[6:7], s[98:99], 0, v[4:5]
	v_lshl_add_u64 v[4:5], s[24:25], 0, v[4:5]
	v_lshl_add_u64 v[72:73], v[4:5], 0, v[38:39]
	v_lshl_add_u64 v[70:71], v[6:7], 0, v[38:39]
	global_load_dwordx4 v[4:7], v[72:73], off offset:16
	global_load_dwordx4 v[12:15], v[70:71], off offset:16
	global_load_dwordx4 v[28:31], v38, s[40:41]
	global_load_dwordx4 v[24:27], v38, s[40:41] offset:128
	global_load_dwordx4 v[20:23], v[72:73], off
	global_load_dwordx4 v[16:19], v[70:71], off
	s_lshl_b32 s22, s48, 7
	s_and_b32 s22, s22, 0x300
	s_add_u32 s19, s19, s22
	s_addc_u32 s21, s21, 0
	s_add_u32 s36, s19, 0x1000
	s_addc_u32 s37, s21, 0
	s_add_u32 s42, s19, 0x1400
	s_addc_u32 s43, s21, 0
	v_lshlrev_b32_e32 v185, 4, v94
	v_and_b32_e32 v186, 63, v94
	s_add_i32 s19, 0, 0x10000
	s_cmp_lg_u32 0, -1
	s_cselect_b32 s21, 0, 0
	s_mov_b32 s72, s73
	s_mov_b32 s74, s73
	s_mov_b32 s75, s73
	s_mov_b32 s76, s73
	s_mov_b32 s77, s73
	s_mov_b32 s78, s73
	s_mov_b32 s79, s73
	s_mov_b32 s80, s73
	s_mov_b32 s81, s73
	s_mov_b32 s82, s73
	s_mov_b32 s83, s73
	s_mov_b32 s84, s73
	s_mov_b32 s85, s73
	s_mov_b32 s86, s73
	s_mov_b32 s87, s73
	v_mov_b32_e32 v189, 0
	s_waitcnt vmcnt(15)
	v_lshlrev_b32_e32 v35, 16, v49
	v_and_b32_e32 v33, 0xffff0000, v49
	v_lshlrev_b32_e32 v41, 16, v48
	s_waitcnt vmcnt(12)
	v_lshlrev_b32_e32 v52, 16, v69
	s_waitcnt vmcnt(9)
	v_and_b32_e32 v119, 0xffff0000, v97
	s_waitcnt vmcnt(7)
	v_lshlrev_b32_e32 v84, 16, v103
	v_and_b32_e32 v86, 0xffff0000, v103
	v_lshlrev_b32_e32 v103, 16, v97
	v_lshlrev_b32_e32 v121, 16, v96
	v_and_b32_e32 v97, 0xffff0000, v96
	v_and_b32_e32 v96, 0xffff0000, v100
	v_and_b32_e32 v50, 0xffff0000, v69
	v_lshlrev_b32_e32 v60, 16, v67
	v_and_b32_e32 v58, 0xffff0000, v67
	v_lshlrev_b32_e32 v69, 16, v83
	v_and_b32_e32 v67, 0xffff0000, v83
	v_lshlrev_b32_e32 v85, 16, v99
	v_mov_b32_e32 v91, v2
	v_and_b32_e32 v87, 0xffff0000, v99
	v_mov_b32_e32 v2, v11
	v_lshlrev_b32_e32 v75, 16, v82
	v_and_b32_e32 v11, 0xffff0000, v82
	v_lshlrev_b32_e32 v79, 16, v81
	s_waitcnt vmcnt(6)
	v_lshlrev_b32_e32 v78, 16, v105
	v_and_b32_e32 v77, 0xffff0000, v81
	v_and_b32_e32 v76, 0xffff0000, v105
	v_lshlrev_b32_e32 v83, 16, v80
	v_lshlrev_b32_e32 v82, 16, v104
	v_and_b32_e32 v81, 0xffff0000, v80
	v_and_b32_e32 v80, 0xffff0000, v104
	v_lshlrev_b32_e32 v105, 16, v98
	v_lshlrev_b32_e32 v104, 16, v102
	v_and_b32_e32 v99, 0xffff0000, v98
	v_and_b32_e32 v98, 0xffff0000, v102
	v_lshlrev_b32_e32 v102, 16, v101
	v_and_b32_e32 v118, 0xffff0000, v101
	v_lshlrev_b32_e32 v120, 16, v100
	v_pk_mul_f32 v[100:101], v[96:97], v[96:97]
	v_lshlrev_b32_e32 v74, 16, v106
	v_pk_fma_f32 v[124:125], v[120:121], v[120:121], v[100:101]
	v_mov_b32_e32 v90, v10
	v_pk_fma_f32 v[124:125], v[102:103], v[102:103], v[124:125]
	v_and_b32_e32 v10, 0xffff0000, v106
	v_pk_fma_f32 v[124:125], v[118:119], v[118:119], v[124:125]
	v_lshlrev_b32_e32 v40, 16, v56
	v_pk_fma_f32 v[124:125], v[104:105], v[104:105], v[124:125]
	v_and_b32_e32 v37, 0xffff0000, v48
	v_pk_fma_f32 v[124:125], v[98:99], v[98:99], v[124:125]
	v_and_b32_e32 v36, 0xffff0000, v56
	v_pk_fma_f32 v[124:125], v[84:85], v[84:85], v[124:125]
	v_lshlrev_b32_e32 v45, 16, v47
	v_pk_fma_f32 v[124:125], v[86:87], v[86:87], v[124:125]
	v_and_b32_e32 v43, 0xffff0000, v47
	v_pk_fma_f32 v[124:125], v[82:83], v[82:83], v[124:125]
	v_lshlrev_b32_e32 v49, 16, v46
	v_pk_fma_f32 v[124:125], v[80:81], v[80:81], v[124:125]
	v_lshlrev_b32_e32 v48, 16, v54
	v_pk_fma_f32 v[124:125], v[78:79], v[78:79], v[124:125]
	v_and_b32_e32 v47, 0xffff0000, v46
	v_pk_fma_f32 v[124:125], v[76:77], v[76:77], v[124:125]
	v_and_b32_e32 v46, 0xffff0000, v54
	v_pk_fma_f32 v[124:125], v[74:75], v[74:75], v[124:125]
	v_lshlrev_b32_e32 v56, 16, v68
	v_and_b32_e32 v54, 0xffff0000, v68
	v_lshlrev_b32_e32 v68, 16, v107
	v_pk_fma_f32 v[124:125], v[10:11], v[10:11], v[124:125]
	v_lshlrev_b32_e32 v34, 16, v57
	v_and_b32_e32 v32, 0xffff0000, v57
	v_lshlrev_b32_e32 v53, 16, v65
	v_and_b32_e32 v51, 0xffff0000, v65
; __device__ __forceinline__ unsigned cvtpk(float lo, float hi) { unsigned r; asm volatile("v_cvt_pk_bf16_f32 %0, %1, %2" : "=v"(r) : "v"(lo), "v"(hi)); return r; }
; __device__ __forceinline__ void attn_body(const bf16_t* Qb, const bf16_t* Kh, const bf16_t* Vh, const bf16_t* Gb, bf16_t* Ob, int seq, char* lds,
;                                           const float* qgain, const float* cosA, const float* sinA, int t0) {
;     ...
;     float ss = 0.f;
; #pragma unroll
;     for (int d0 = 0; d0 < 8; ++d0)
; #pragma unroll
;       for (int e = 0; e < 8; ++e) { const float v = bf2f((unsigned short)qr[d0][e]); ss += v * v; }
;     { auto rr = __builtin_amdgcn_permlane32_swap(__float_as_uint(ss), __float_as_uint(ss), false, false); ss = __uint_as_float(rr[0]) + __uint_as_float(rr[1]); }
;     const float rinv = __builtin_amdgcn_rsqf(ss * (1.f / 128) + RMS_EPS);
;     const int t = t0 + wid * QBLK + r32, rp = t >> 6, cp = t & 63;
; #pragma unroll
;     for (int half = 0; half < 2; ++half) { const int pos = half ? cp : rp;
; #pragma unroll
;       for (int dd = 0; dd < 2; ++dd) { const int dx = 4 * half + dd, dy = dx + 2, i0 = 16 * dd + 8 * hi;
;         const f32x4 c0 = *(const f32x4*)(cosA + pos * 32 + i0), c1 = *(const f32x4*)(cosA + pos * 32 + i0 + 4), s0 = *(const f32x4*)(sinA + pos * 32 + i0), s1 = *(const f32x4*)(sinA + pos * 32 + i0 + 4);
;         const f32x4 gx0 = *(const f32x4*)(qgain + 16 * dx + 8 * hi), gx1 = *(const f32x4*)(qgain + 16 * dx + 8 * hi + 4), gy0 = *(const f32x4*)(qgain + 16 * dy + 8 * hi), gy1 = *(const f32x4*)(qgain + 16 * dy + 8 * hi + 4);
;         float xo[8], yo[8];
; #pragma unroll
;         for (int e = 0; e < 8; ++e) { const float cc = e < 4 ? c0[e & 3] : c1[e & 3], sn = e < 4 ? s0[e & 3] : s1[e & 3];
;           const float x = bf2f((unsigned short)qr[dx][e]) * rinv * (e < 4 ? gx0[e & 3] : gx1[e & 3]), y = bf2f((unsigned short)qr[dy][e]) * rinv * (e < 4 ? gy0[e & 3] : gy1[e & 3]);
;           xo[e] = x * cc - y * sn; yo[e] = y * cc + x * sn; }
;         u32x4 wx = {cvtpk(xo[0], xo[1]), cvtpk(xo[2], xo[3]), cvtpk(xo[4], xo[5]), cvtpk(xo[6], xo[7])}, wy = {cvtpk(yo[0], yo[1]), cvtpk(yo[2], yo[3]), cvtpk(yo[4], yo[5]), cvtpk(yo[6], yo[7])};
;         qr[dx] = *reinterpret_cast<bf16x8*>(&wx); qr[dy] = *reinterpret_cast<bf16x8*>(&wy); } }
	v_lshlrev_b32_e32 v44, 16, v55
	v_and_b32_e32 v42, 0xffff0000, v55
	v_lshlrev_b32_e32 v57, 16, v64
	v_and_b32_e32 v55, 0xffff0000, v64
	v_lshlrev_b32_e32 v61, 16, v63
	v_and_b32_e32 v59, 0xffff0000, v63
	v_lshlrev_b32_e32 v65, 16, v62
	v_lshlrev_b32_e32 v64, 16, v66
	v_and_b32_e32 v63, 0xffff0000, v62
	v_and_b32_e32 v62, 0xffff0000, v66
	v_and_b32_e32 v66, 0xffff0000, v107
	v_pk_fma_f32 v[124:125], v[68:69], v[68:69], v[124:125]
	v_mov_b32_e32 v107, v0
	v_pk_fma_f32 v[124:125], v[66:67], v[66:67], v[124:125]
	v_mul_f32_e32 v0, v121, v121
	v_pk_add_f32 v[124:125], v[0:1], v[124:125] op_sel_hi:[0,1]
	v_pk_add_f32 v[100:101], v[100:101], v[124:125] op_sel:[1,0] op_sel_hi:[0,1]
	v_mul_f32_e32 v0, v103, v103
	v_pk_add_f32 v[100:101], v[0:1], v[100:101] op_sel_hi:[0,1]
	v_mul_f32_e32 v0, v119, v119
	v_pk_add_f32 v[100:101], v[0:1], v[100:101] op_sel_hi:[0,1]
	v_mul_f32_e32 v0, v105, v105
	v_pk_add_f32 v[100:101], v[0:1], v[100:101] op_sel_hi:[0,1]
	v_mul_f32_e32 v0, v99, v99
	v_pk_add_f32 v[100:101], v[0:1], v[100:101] op_sel_hi:[0,1]
	v_mul_f32_e32 v0, v85, v85
	v_pk_add_f32 v[100:101], v[0:1], v[100:101] op_sel_hi:[0,1]
	v_mul_f32_e32 v0, v87, v87
	v_pk_add_f32 v[100:101], v[0:1], v[100:101] op_sel_hi:[0,1]
	v_mul_f32_e32 v0, v83, v83
	v_pk_add_f32 v[100:101], v[0:1], v[100:101] op_sel_hi:[0,1]
	v_mul_f32_e32 v0, v81, v81
	v_pk_add_f32 v[100:101], v[0:1], v[100:101] op_sel_hi:[0,1]
	v_mul_f32_e32 v0, v79, v79
	v_pk_add_f32 v[100:101], v[0:1], v[100:101] op_sel_hi:[0,1]
	v_mul_f32_e32 v0, v77, v77
	v_pk_add_f32 v[100:101], v[0:1], v[100:101] op_sel_hi:[0,1]
	v_mul_f32_e32 v0, v75, v75
	v_pk_add_f32 v[100:101], v[0:1], v[100:101] op_sel_hi:[0,1]
	v_mul_f32_e32 v0, v11, v11
	v_pk_add_f32 v[100:101], v[0:1], v[100:101] op_sel_hi:[0,1]
	v_mul_f32_e32 v0, v69, v69
	v_pk_add_f32 v[100:101], v[0:1], v[100:101] op_sel_hi:[0,1]
	v_mul_f32_e32 v0, v67, v67
	v_pk_add_f32 v[100:101], v[0:1], v[100:101] op_sel_hi:[0,1]
	v_pk_fma_f32 v[100:101], v[64:65], v[64:65], v[100:101]
	v_mul_f32_e32 v0, v65, v65
	v_pk_fma_f32 v[100:101], v[62:63], v[62:63], v[100:101]
	v_mov_b32_e32 v110, v37
	v_pk_fma_f32 v[100:101], v[60:61], v[60:61], v[100:101]
	v_mov_b32_e32 v111, v41
	v_pk_fma_f32 v[100:101], v[58:59], v[58:59], v[100:101]
	v_mov_b32_e32 v108, v33
	v_pk_fma_f32 v[100:101], v[56:57], v[56:57], v[100:101]
	v_mov_b32_e32 v109, v35
	v_pk_fma_f32 v[100:101], v[54:55], v[54:55], v[100:101]
	v_mov_b32_e32 v106, v8
	v_pk_fma_f32 v[100:101], v[52:53], v[52:53], v[100:101]
	s_waitcnt vmcnt(2)
	v_mov_b32_e32 v123, v24
	v_pk_fma_f32 v[100:101], v[50:51], v[50:51], v[100:101]
	v_mov_b32_e32 v24, v29
	v_pk_fma_f32 v[100:101], v[48:49], v[48:49], v[100:101]
	v_mov_b32_e32 v114, v30
	v_pk_fma_f32 v[100:101], v[46:47], v[46:47], v[100:101]
	v_mov_b32_e32 v115, v26
	v_pk_fma_f32 v[100:101], v[44:45], v[44:45], v[100:101]
	v_mov_b32_e32 v122, v28
	v_pk_fma_f32 v[100:101], v[42:43], v[42:43], v[100:101]
	s_waitcnt vmcnt(1)
	v_mov_b32_e32 v116, v22
	v_pk_fma_f32 v[100:101], v[40:41], v[40:41], v[100:101]
	s_waitcnt vmcnt(0)
	v_mov_b32_e32 v117, v18
	v_pk_fma_f32 v[100:101], v[36:37], v[36:37], v[100:101]
	v_mov_b32_e32 v26, v31
	v_pk_fma_f32 v[100:101], v[34:35], v[34:35], v[100:101]
	v_mov_b32_e32 v112, v4
	v_pk_fma_f32 v[100:101], v[32:33], v[32:33], v[100:101]
	v_mov_b32_e32 v113, v12
	v_pk_add_f32 v[100:101], v[0:1], v[100:101] op_sel_hi:[0,1]
	v_mul_f32_e32 v0, v63, v63
	v_pk_add_f32 v[100:101], v[0:1], v[100:101] op_sel_hi:[0,1]
	v_mul_f32_e32 v0, v61, v61
	v_pk_add_f32 v[100:101], v[0:1], v[100:101] op_sel_hi:[0,1]
	v_mul_f32_e32 v0, v59, v59
	v_pk_add_f32 v[100:101], v[0:1], v[100:101] op_sel_hi:[0,1]
	v_mul_f32_e32 v0, v57, v57
	v_pk_add_f32 v[100:101], v[0:1], v[100:101] op_sel_hi:[0,1]
	v_mul_f32_e32 v0, v55, v55
	v_pk_add_f32 v[100:101], v[0:1], v[100:101] op_sel_hi:[0,1]
	v_mul_f32_e32 v0, v53, v53
	v_pk_add_f32 v[100:101], v[0:1], v[100:101] op_sel_hi:[0,1]
	v_mul_f32_e32 v0, v51, v51
	v_pk_add_f32 v[100:101], v[0:1], v[100:101] op_sel_hi:[0,1]
	v_mul_f32_e32 v0, v49, v49
	v_pk_add_f32 v[100:101], v[0:1], v[100:101] op_sel_hi:[0,1]
	v_mul_f32_e32 v0, v47, v47
	v_pk_add_f32 v[100:101], v[0:1], v[100:101] op_sel_hi:[0,1]
	v_mul_f32_e32 v0, v45, v45
	v_pk_add_f32 v[100:101], v[0:1], v[100:101] op_sel_hi:[0,1]
	v_mul_f32_e32 v0, v43, v43
	v_pk_add_f32 v[100:101], v[0:1], v[100:101] op_sel_hi:[0,1]
	v_mul_f32_e32 v0, v41, v41
	v_pk_add_f32 v[100:101], v[0:1], v[100:101] op_sel_hi:[0,1]
	v_pk_fma_f32 v[100:101], v[110:111], v[110:111], v[100:101]
	v_mul_f32_e32 v0, v35, v35
	v_pk_add_f32 v[100:101], v[0:1], v[100:101] op_sel_hi:[0,1]
	v_pk_fma_f32 v[100:101], v[108:109], v[108:109], v[100:101]
	v_mov_b32_e32 v110, v16
	v_mov_b32_e32 v0, v100
	s_nop 1
	v_permlane32_swap_b32_e32 v100, v0
	v_add_f32_e32 v0, v100, v0
	v_fmamk_f32 v0, v0, 0x3c000000, v244
	v_rsq_f32_e32 v8, v0
	v_mov_b32_e32 v101, v16
	v_mov_b32_e32 v16, v21
	v_mov_b32_e32 v100, v20
	v_pk_mul_f32 v[96:97], v[8:9], v[96:97] op_sel_hi:[0,1]
	v_pk_mul_f32 v[24:25], v[24:25], v[96:97]
	v_mov_b32_e32 v111, v20
	v_mov_b32_e32 v20, v17
	v_pk_mul_f32 v[16:17], v[16:17], v[24:25]
	v_pk_mul_f32 v[28:29], v[20:21], v[24:25]
	v_add_f32_e32 v24, v16, v17
	v_pk_mul_f32 v[16:17], v[8:9], v[102:103] op_sel_hi:[0,1]
	v_pk_mul_f32 v[16:17], v[114:115], v[16:17]
	v_mov_b32_e32 v20, v18
	v_mov_b32_e32 v21, v22
	v_pk_mul_f32 v[20:21], v[20:21], v[16:17]
	v_pk_mul_f32 v[16:17], v[116:117], v[16:17]
	v_sub_f32_e32 v28, v28, v29
	v_add_f32_e32 v29, v16, v17
	v_pk_mul_f32 v[16:17], v[8:9], v[118:119] op_sel_hi:[0,1]
	v_pk_mul_f32 v[16:17], v[26:27], v[16:17]
	v_mov_b32_e32 v22, v19
	v_mov_b32_e32 v18, v23
	v_sub_f32_e32 v25, v20, v21
; __device__ __forceinline__ unsigned cvtpk(float lo, float hi) { unsigned r; asm volatile("v_cvt_pk_bf16_f32 %0, %1, %2" : "=v"(r) : "v"(lo), "v"(hi)); return r; }
; __device__ __forceinline__ unsigned cvtpk(float lo, float hi) { unsigned r; asm volatile("v_cvt_pk_bf16_f32 %0, %1, %2" : "=v"(r) : "v"(lo), "v"(hi)); return r; }
; __device__ __forceinline__ void attn_body(const bf16_t* Qb, const bf16_t* Kh, const bf16_t* Vh, const bf16_t* Gb, bf16_t* Ob, int seq, char* lds,
;                                           const float* qgain, const float* cosA, const float* sinA, int t0) {
;     ...
;     for (int half = 0; half < 2; ++half) { const int pos = half ? cp : rp;
; #pragma unroll
;       for (int dd = 0; dd < 2; ++dd) { const int dx = 4 * half + dd, dy = dx + 2, i0 = 16 * dd + 8 * hi;
;         const f32x4 c0 = *(const f32x4*)(cosA + pos * 32 + i0), c1 = *(const f32x4*)(cosA + pos * 32 + i0 + 4), s0 = *(const f32x4*)(sinA + pos * 32 + i0), s1 = *(const f32x4*)(sinA + pos * 32 + i0 + 4);
;         const f32x4 gx0 = *(const f32x4*)(qgain + 16 * dx + 8 * hi), gx1 = *(const f32x4*)(qgain + 16 * dx + 8 * hi + 4), gy0 = *(const f32x4*)(qgain + 16 * dy + 8 * hi), gy1 = *(const f32x4*)(qgain + 16 * dy + 8 * hi + 4);
;         float xo[8], yo[8];
; #pragma unroll
;         for (int e = 0; e < 8; ++e) { const float cc = e < 4 ? c0[e & 3] : c1[e & 3], sn = e < 4 ? s0[e & 3] : s1[e & 3];
;           const float x = bf2f((unsigned short)qr[dx][e]) * rinv * (e < 4 ? gx0[e & 3] : gx1[e & 3]), y = bf2f((unsigned short)qr[dy][e]) * rinv * (e < 4 ? gy0[e & 3] : gy1[e & 3]);
;           xo[e] = x * cc - y * sn; yo[e] = y * cc + x * sn; }
;         u32x4 wx = {cvtpk(xo[0], xo[1]), cvtpk(xo[2], xo[3]), cvtpk(xo[4], xo[5]), cvtpk(xo[6], xo[7])}, wy = {cvtpk(yo[0], yo[1]), cvtpk(yo[2], yo[3]), cvtpk(yo[4], yo[5]), cvtpk(yo[6], yo[7])};
;         qr[dx] = *reinterpret_cast<bf16x8*>(&wx); qr[dy] = *reinterpret_cast<bf16x8*>(&wy); } }
	v_pk_mul_f32 v[20:21], v[22:23], v[16:17]
	v_pk_mul_f32 v[16:17], v[18:19], v[16:17]
	v_sub_f32_e32 v20, v20, v21
	v_add_f32_e32 v21, v16, v17
	v_pk_mul_f32 v[16:17], v[8:9], v[104:105] op_sel_hi:[0,1]
	v_pk_mul_f32 v[16:17], v[16:17], v[106:107]
	v_mov_b32_e32 v18, v12
	v_mov_b32_e32 v19, v4
	v_pk_mul_f32 v[18:19], v[18:19], v[16:17]
	v_pk_mul_f32 v[16:17], v[112:113], v[16:17]
	v_sub_f32_e32 v18, v18, v19
	v_add_f32_e32 v19, v16, v17
	v_pk_mul_f32 v[16:17], v[8:9], v[98:99] op_sel_hi:[0,1]
	v_mov_b32_e32 v0, v9
	v_pk_mul_f32 v[0:1], v[16:17], v[0:1]
	v_mov_b32_e32 v4, v13
	v_pk_mul_f32 v[16:17], v[4:5], v[0:1]
	v_mov_b32_e32 v12, v5
	v_pk_mul_f32 v[108:109], v[8:9], v[120:121] op_sel_hi:[0,1]
	v_sub_f32_e32 v9, v16, v17
	v_pk_mul_f32 v[0:1], v[12:13], v[0:1]
	v_mov_b32_e32 v88, v6
	v_add_f32_e32 v12, v0, v1
	v_pk_mul_f32 v[0:1], v[8:9], v[84:85] op_sel_hi:[0,1]
	v_mov_b32_e32 v89, v14
	v_pk_mul_f32 v[0:1], v[0:1], v[90:91]
	v_mov_b32_e32 v4, v14
	v_mov_b32_e32 v5, v6
	v_pk_mul_f32 v[4:5], v[4:5], v[0:1]
	v_pk_mul_f32 v[0:1], v[88:89], v[0:1]
	v_sub_f32_e32 v4, v4, v5
	v_add_f32_e32 v5, v0, v1
	v_pk_mul_f32 v[0:1], v[8:9], v[86:87] op_sel_hi:[0,1]
	v_pk_mul_f32 v[108:109], v[122:123], v[108:109]
	v_pk_mul_f32 v[0:1], v[0:1], v[2:3]
	v_mov_b32_e32 v6, v15
	v_mov_b32_e32 v92, v7
	v_mov_b32_e32 v93, v15
	v_pk_mul_f32 v[110:111], v[110:111], v[108:109]
	v_pk_mul_f32 v[2:3], v[6:7], v[0:1]
	v_sub_f32_e32 v30, v110, v111
	v_pk_mul_f32 v[100:101], v[100:101], v[108:109]
	v_sub_f32_e32 v2, v2, v3
	v_pk_mul_f32 v[0:1], v[92:93], v[0:1]
	v_add_f32_e32 v108, v100, v101
	v_add_f32_e32 v0, v0, v1
	v_cvt_pk_bf16_f32 v100, v30, v28
	v_cvt_pk_bf16_f32 v101, v25, v20
	v_cvt_pk_bf16_f32 v102, v18, v9
	v_cvt_pk_bf16_f32 v103, v4, v2
	v_cvt_pk_bf16_f32 v96, v108, v24
	v_cvt_pk_bf16_f32 v97, v29, v21
	v_cvt_pk_bf16_f32 v98, v19, v12
	v_cvt_pk_bf16_f32 v99, v5, v0
	global_load_dwordx4 v[2:5], v38, s[40:41] offset:64
	global_load_dwordx4 v[12:15], v38, s[40:41] offset:192
	global_load_dwordx4 v[16:19], v[70:71], off offset:64
	global_load_dwordx4 v[20:23], v[72:73], off offset:64
	global_load_dwordx4 v[24:27], v38, s[40:41] offset:80
	global_load_dwordx4 v[28:31], v38, s[40:41] offset:208
	global_load_dwordx4 v[84:87], v[70:71], off offset:80
	s_nop 0
	global_load_dwordx4 v[70:73], v[72:73], off offset:80
	v_lshlrev_b32_e32 v0, 7, v95
	v_and_b32_e32 v0, 0x1f80, v0
	v_mov_b32_e32 v1, v177
	v_lshl_add_u64 v[6:7], s[98:99], 0, v[0:1]
	v_lshl_add_u64 v[88:89], s[24:25], 0, v[0:1]
	v_lshl_add_u64 v[0:1], v[6:7], 0, v[38:39]
	v_pk_mul_f32 v[6:7], v[8:9], v[82:83] op_sel_hi:[0,1]
	s_waitcnt vmcnt(7)
	v_mov_b32_e32 v82, v2
	s_waitcnt vmcnt(6)
	v_mov_b32_e32 v83, v12
	v_pk_mul_f32 v[6:7], v[6:7], v[82:83]
	s_waitcnt vmcnt(5)
	v_mov_b32_e32 v82, v16
	s_waitcnt vmcnt(4)
	v_mov_b32_e32 v83, v20
	v_pk_mul_f32 v[82:83], v[82:83], v[6:7]
	v_mov_b32_e32 v12, v3
	v_sub_f32_e32 v9, v82, v83
	v_mov_b32_e32 v82, v20
	v_mov_b32_e32 v83, v16
	v_pk_mul_f32 v[6:7], v[82:83], v[6:7]
	v_mov_b32_e32 v20, v17
	v_add_f32_e32 v82, v6, v7
	v_pk_mul_f32 v[6:7], v[8:9], v[80:81] op_sel_hi:[0,1]
	v_pk_mul_f32 v[2:3], v[6:7], v[12:13]
	v_mov_b32_e32 v16, v21
	v_pk_mul_f32 v[6:7], v[20:21], v[2:3]
	v_pk_mul_f32 v[2:3], v[16:17], v[2:3]
	v_sub_f32_e32 v12, v6, v7
	v_add_f32_e32 v13, v2, v3
	v_pk_mul_f32 v[2:3], v[8:9], v[78:79] op_sel_hi:[0,1]
	v_mov_b32_e32 v6, v4
	v_mov_b32_e32 v7, v14
	v_pk_mul_f32 v[2:3], v[2:3], v[6:7]
	v_mov_b32_e32 v6, v18
	v_mov_b32_e32 v7, v22
	v_pk_mul_f32 v[6:7], v[6:7], v[2:3]
	v_mov_b32_e32 v14, v5
	v_sub_f32_e32 v16, v6, v7
	v_mov_b32_e32 v6, v22
	v_mov_b32_e32 v7, v18
	v_pk_mul_f32 v[2:3], v[6:7], v[2:3]
	v_mov_b32_e32 v22, v19
	v_add_f32_e32 v6, v2, v3
	v_pk_mul_f32 v[2:3], v[8:9], v[76:77] op_sel_hi:[0,1]
	v_pk_mul_f32 v[2:3], v[2:3], v[14:15]
	v_mov_b32_e32 v18, v23
	v_pk_mul_f32 v[4:5], v[22:23], v[2:3]
	v_pk_mul_f32 v[2:3], v[18:19], v[2:3]
	v_sub_f32_e32 v7, v4, v5
	v_add_f32_e32 v14, v2, v3
	v_pk_mul_f32 v[2:3], v[8:9], v[74:75] op_sel_hi:[0,1]
	s_waitcnt vmcnt(3)
	v_mov_b32_e32 v4, v24
	s_waitcnt vmcnt(2)
	v_mov_b32_e32 v5, v28
	v_pk_mul_f32 v[2:3], v[2:3], v[4:5]
	s_waitcnt vmcnt(1)
	v_mov_b32_e32 v4, v84
	s_waitcnt vmcnt(0)
	v_mov_b32_e32 v5, v70
	v_pk_mul_f32 v[4:5], v[4:5], v[2:3]
	v_mov_b32_e32 v28, v25
	v_sub_f32_e32 v15, v4, v5
	v_mov_b32_e32 v4, v70
	v_mov_b32_e32 v5, v84
	v_pk_mul_f32 v[2:3], v[4:5], v[2:3]
	v_mov_b32_e32 v70, v85
	v_add_f32_e32 v17, v2, v3
	v_pk_mul_f32 v[2:3], v[8:9], v[10:11] op_sel_hi:[0,1]
	v_pk_mul_f32 v[2:3], v[2:3], v[28:29]
	v_mov_b32_e32 v84, v71
	v_pk_mul_f32 v[4:5], v[70:71], v[2:3]
	v_pk_mul_f32 v[2:3], v[84:85], v[2:3]
	v_sub_f32_e32 v10, v4, v5
	v_add_f32_e32 v11, v2, v3
	v_pk_mul_f32 v[2:3], v[8:9], v[68:69] op_sel_hi:[0,1]
	v_mov_b32_e32 v4, v26
	v_mov_b32_e32 v5, v30
	v_pk_mul_f32 v[2:3], v[2:3], v[4:5]
	v_mov_b32_e32 v4, v86
	v_mov_b32_e32 v5, v72
	v_pk_mul_f32 v[4:5], v[4:5], v[2:3]
	v_mov_b32_e32 v30, v27
	v_sub_f32_e32 v18, v4, v5
	v_mov_b32_e32 v4, v72
	v_mov_b32_e32 v5, v86
	v_pk_mul_f32 v[2:3], v[4:5], v[2:3]
	v_mov_b32_e32 v72, v87
	v_add_f32_e32 v19, v2, v3
	v_pk_mul_f32 v[2:3], v[8:9], v[66:67] op_sel_hi:[0,1]
	v_pk_mul_f32 v[2:3], v[2:3], v[30:31]
	v_mov_b32_e32 v86, v73
	v_pk_mul_f32 v[4:5], v[72:73], v[2:3]
	v_pk_mul_f32 v[2:3], v[86:87], v[2:3]
	v_sub_f32_e32 v4, v4, v5
	v_add_f32_e32 v2, v2, v3
	v_cvt_pk_bf16_f32 v108, v9, v12
	v_cvt_pk_bf16_f32 v109, v16, v7
	v_cvt_pk_bf16_f32 v110, v15, v10
	v_cvt_pk_bf16_f32 v111, v18, v4
	v_cvt_pk_bf16_f32 v104, v82, v13
	v_cvt_pk_bf16_f32 v105, v6, v14
	v_cvt_pk_bf16_f32 v106, v17, v11
	v_cvt_pk_bf16_f32 v107, v19, v2
	global_load_dwordx4 v[2:5], v38, s[40:41] offset:256
	global_load_dwordx4 v[10:13], v38, s[40:41] offset:384
	v_lshl_add_u64 v[6:7], v[88:89], 0, v[38:39]
	global_load_dwordx4 v[14:17], v[0:1], off
	global_load_dwordx4 v[18:21], v[6:7], off
	global_load_dwordx4 v[22:25], v38, s[40:41] offset:272
	global_load_dwordx4 v[26:29], v38, s[40:41] offset:400
	global_load_dwordx4 v[66:69], v[0:1], off offset:16
	global_load_dwordx4 v[70:73], v[6:7], off offset:16
	v_pk_mul_f32 v[30:31], v[8:9], v[64:65] op_sel_hi:[0,1]
	s_waitcnt vmcnt(7)
; __device__ __forceinline__ unsigned cvtpk(float lo, float hi) { unsigned r; asm volatile("v_cvt_pk_bf16_f32 %0, %1, %2" : "=v"(r) : "v"(lo), "v"(hi)); return r; }
; __device__ __forceinline__ int v_st(int k, int c) { const int kk = (k & ~0xC) | ((k & 4) << 1) | ((k & 8) >> 1); return ((kk >> 3) * 4 + (c >> 5)) * 512 + ((kk & 7) * 32 + (c & 31)) * 2; }
; __device__ __forceinline__ int v_rd_base(int lane) { return ((lane & 3) << 3) | (((lane >> 2) & 3) << 6) | (((lane >> 4) & 1) << 5) | (((lane >> 5) & 1) << 8); }
; __device__ __forceinline__ void attn_body(const bf16_t* Qb, const bf16_t* Kh, const bf16_t* Vh, const bf16_t* Gb, bf16_t* Ob, int seq, char* lds,
;                                           const float* qgain, const float* cosA, const float* sinA, int t0) {
;     ...
;     for (int half = 0; half < 2; ++half) { const int pos = half ? cp : rp;
; #pragma unroll
;       for (int dd = 0; dd < 2; ++dd) { const int dx = 4 * half + dd, dy = dx + 2, i0 = 16 * dd + 8 * hi;
;         const f32x4 c0 = *(const f32x4*)(cosA + pos * 32 + i0), c1 = *(const f32x4*)(cosA + pos * 32 + i0 + 4), s0 = *(const f32x4*)(sinA + pos * 32 + i0), s1 = *(const f32x4*)(sinA + pos * 32 + i0 + 4);
;         const f32x4 gx0 = *(const f32x4*)(qgain + 16 * dx + 8 * hi), gx1 = *(const f32x4*)(qgain + 16 * dx + 8 * hi + 4), gy0 = *(const f32x4*)(qgain + 16 * dy + 8 * hi), gy1 = *(const f32x4*)(qgain + 16 * dy + 8 * hi + 4);
;         float xo[8], yo[8];
; #pragma unroll
;         for (int e = 0; e < 8; ++e) { const float cc = e < 4 ? c0[e & 3] : c1[e & 3], sn = e < 4 ? s0[e & 3] : s1[e & 3];
;           const float x = bf2f((unsigned short)qr[dx][e]) * rinv * (e < 4 ? gx0[e & 3] : gx1[e & 3]), y = bf2f((unsigned short)qr[dy][e]) * rinv * (e < 4 ? gy0[e & 3] : gy1[e & 3]);
;           xo[e] = x * cc - y * sn; yo[e] = y * cc + x * sn; }
;         u32x4 wx = {cvtpk(xo[0], xo[1]), cvtpk(xo[2], xo[3]), cvtpk(xo[4], xo[5]), cvtpk(xo[6], xo[7])}, wy = {cvtpk(yo[0], yo[1]), cvtpk(yo[2], yo[3]), cvtpk(yo[4], yo[5]), cvtpk(yo[6], yo[7])};
;         qr[dx] = *reinterpret_cast<bf16x8*>(&wx); qr[dy] = *reinterpret_cast<bf16x8*>(&wy); } }
;     ...
;   const int sr = tid >> 4, sc = (tid & 15) * 8, vst0 = v_st(sr, sc), vst1 = v_st(32 + sr, sc);
;   const int vb0 = (int)(uintptr_t)V_lds + v_rd_base(lane);
;   struct { bf16x8 vs0, vs1, ks0, ks1; } sr_[2];
	v_mov_b32_e32 v64, v2
	s_waitcnt vmcnt(6)
	v_mov_b32_e32 v65, v10
	v_pk_mul_f32 v[30:31], v[30:31], v[64:65]
	s_waitcnt vmcnt(5)
	v_mov_b32_e32 v64, v14
	s_waitcnt vmcnt(4)
	v_mov_b32_e32 v65, v18
	v_pk_mul_f32 v[64:65], v[64:65], v[30:31]
	v_mov_b32_e32 v10, v3
	v_sub_f32_e32 v9, v64, v65
	v_mov_b32_e32 v64, v18
	v_mov_b32_e32 v65, v14
	v_pk_mul_f32 v[30:31], v[64:65], v[30:31]
	v_mov_b32_e32 v18, v15
	v_add_f32_e32 v39, v30, v31
	v_pk_mul_f32 v[30:31], v[8:9], v[62:63] op_sel_hi:[0,1]
	v_pk_mul_f32 v[2:3], v[30:31], v[10:11]
	v_mov_b32_e32 v14, v19
	v_pk_mul_f32 v[10:11], v[18:19], v[2:3]
	v_pk_mul_f32 v[2:3], v[14:15], v[2:3]
	v_sub_f32_e32 v18, v10, v11
	v_add_f32_e32 v14, v2, v3
	v_pk_mul_f32 v[2:3], v[8:9], v[60:61] op_sel_hi:[0,1]
	v_mov_b32_e32 v10, v4
	v_mov_b32_e32 v11, v12
	v_pk_mul_f32 v[2:3], v[2:3], v[10:11]
	v_mov_b32_e32 v10, v16
	v_mov_b32_e32 v11, v20
	v_pk_mul_f32 v[10:11], v[10:11], v[2:3]
	v_mov_b32_e32 v12, v5
	v_sub_f32_e32 v15, v10, v11
	v_mov_b32_e32 v10, v20
	v_mov_b32_e32 v11, v16
	v_pk_mul_f32 v[2:3], v[10:11], v[2:3]
	v_mov_b32_e32 v20, v17
	v_add_f32_e32 v10, v2, v3
	v_pk_mul_f32 v[2:3], v[8:9], v[58:59] op_sel_hi:[0,1]
	v_pk_mul_f32 v[2:3], v[2:3], v[12:13]
	v_mov_b32_e32 v16, v21
	v_pk_mul_f32 v[4:5], v[20:21], v[2:3]
	v_pk_mul_f32 v[2:3], v[16:17], v[2:3]
	v_sub_f32_e32 v11, v4, v5
	v_add_f32_e32 v12, v2, v3
	v_pk_mul_f32 v[2:3], v[8:9], v[56:57] op_sel_hi:[0,1]
	s_waitcnt vmcnt(3)
	v_mov_b32_e32 v4, v22
	s_waitcnt vmcnt(2)
	v_mov_b32_e32 v5, v26
	v_pk_mul_f32 v[2:3], v[2:3], v[4:5]
	s_waitcnt vmcnt(1)
	v_mov_b32_e32 v4, v66
	s_waitcnt vmcnt(0)
	v_mov_b32_e32 v5, v70
	v_pk_mul_f32 v[4:5], v[4:5], v[2:3]
	v_mov_b32_e32 v26, v23
	v_sub_f32_e32 v13, v4, v5
	v_mov_b32_e32 v4, v70
	v_mov_b32_e32 v5, v66
	v_pk_mul_f32 v[2:3], v[4:5], v[2:3]
	v_mov_b32_e32 v70, v67
	v_add_f32_e32 v16, v2, v3
	v_pk_mul_f32 v[2:3], v[8:9], v[54:55] op_sel_hi:[0,1]
	v_pk_mul_f32 v[2:3], v[2:3], v[26:27]
	v_mov_b32_e32 v66, v71
	v_pk_mul_f32 v[4:5], v[70:71], v[2:3]
	v_pk_mul_f32 v[2:3], v[66:67], v[2:3]
	v_sub_f32_e32 v17, v4, v5
	v_add_f32_e32 v19, v2, v3
	v_pk_mul_f32 v[2:3], v[8:9], v[52:53] op_sel_hi:[0,1]
	v_mov_b32_e32 v4, v24
	v_mov_b32_e32 v5, v28
	v_pk_mul_f32 v[2:3], v[2:3], v[4:5]
	v_mov_b32_e32 v4, v68
	v_mov_b32_e32 v5, v72
	v_pk_mul_f32 v[4:5], v[4:5], v[2:3]
	v_mov_b32_e32 v28, v25
	v_sub_f32_e32 v20, v4, v5
	v_mov_b32_e32 v4, v72
	v_mov_b32_e32 v5, v68
	v_pk_mul_f32 v[2:3], v[4:5], v[2:3]
	v_mov_b32_e32 v72, v69
	v_add_f32_e32 v21, v2, v3
	v_pk_mul_f32 v[2:3], v[8:9], v[50:51] op_sel_hi:[0,1]
	v_pk_mul_f32 v[2:3], v[2:3], v[28:29]
	v_mov_b32_e32 v68, v73
	v_pk_mul_f32 v[4:5], v[72:73], v[2:3]
	v_pk_mul_f32 v[2:3], v[68:69], v[2:3]
	v_sub_f32_e32 v4, v4, v5
	v_add_f32_e32 v2, v2, v3
	v_cvt_pk_bf16_f32 v116, v9, v18
	v_cvt_pk_bf16_f32 v117, v15, v11
	v_cvt_pk_bf16_f32 v118, v13, v17
	v_cvt_pk_bf16_f32 v119, v20, v4
	v_cvt_pk_bf16_f32 v112, v39, v14
	v_cvt_pk_bf16_f32 v113, v10, v12
	v_cvt_pk_bf16_f32 v114, v16, v19
	v_cvt_pk_bf16_f32 v115, v21, v2
	global_load_dwordx4 v[2:5], v38, s[40:41] offset:320
	global_load_dwordx4 v[10:13], v38, s[40:41] offset:448
	global_load_dwordx4 v[14:17], v[0:1], off offset:64
	global_load_dwordx4 v[18:21], v[6:7], off offset:64
	global_load_dwordx4 v[22:25], v38, s[40:41] offset:336
	global_load_dwordx4 v[26:29], v38, s[40:41] offset:464
	global_load_dwordx4 v[50:53], v[0:1], off offset:80
	global_load_dwordx4 v[54:57], v[6:7], off offset:80
	v_pk_mul_f32 v[0:1], v[8:9], v[48:49] op_sel_hi:[0,1]
	v_ashrrev_i32_e32 v48, 4, v94
	v_add_u32_e32 v66, 0x80, v48
	v_mad_i64_i32 v[66:67], s[22:23], v66, s69, 0
	v_add_u32_e32 v70, 0xa0, v48
	v_mad_i64_i32 v[70:71], s[22:23], v70, s69, 0
	v_ashrrev_i32_e32 v49, 31, v48
	s_waitcnt vmcnt(7)
	v_mov_b32_e32 v6, v2
	s_waitcnt vmcnt(6)
	v_mov_b32_e32 v7, v10
	v_pk_mul_f32 v[0:1], v[0:1], v[6:7]
	s_waitcnt vmcnt(5)
	v_mov_b32_e32 v6, v14
	s_waitcnt vmcnt(4)
	v_mov_b32_e32 v7, v18
	v_pk_mul_f32 v[6:7], v[6:7], v[0:1]
	v_mov_b32_e32 v10, v3
	v_sub_f32_e32 v9, v6, v7
	v_mov_b32_e32 v6, v18
	v_mov_b32_e32 v7, v14
	v_pk_mul_f32 v[0:1], v[6:7], v[0:1]
	v_mov_b32_e32 v18, v15
	v_add_f32_e32 v6, v0, v1
	v_pk_mul_f32 v[0:1], v[8:9], v[46:47] op_sel_hi:[0,1]
	v_pk_mul_f32 v[0:1], v[0:1], v[10:11]
	v_mov_b32_e32 v14, v19
	v_pk_mul_f32 v[2:3], v[18:19], v[0:1]
	v_pk_mul_f32 v[0:1], v[14:15], v[0:1]
	v_sub_f32_e32 v7, v2, v3
	v_add_f32_e32 v10, v0, v1
	v_pk_mul_f32 v[0:1], v[8:9], v[44:45] op_sel_hi:[0,1]
	v_mov_b32_e32 v2, v4
	v_mov_b32_e32 v3, v12
	v_pk_mul_f32 v[0:1], v[0:1], v[2:3]
	v_mov_b32_e32 v2, v16
	v_mov_b32_e32 v3, v20
	v_pk_mul_f32 v[2:3], v[2:3], v[0:1]
	v_mov_b32_e32 v12, v5
	v_sub_f32_e32 v4, v2, v3
	v_mov_b32_e32 v2, v20
	v_mov_b32_e32 v3, v16
	v_pk_mul_f32 v[0:1], v[2:3], v[0:1]
	v_mov_b32_e32 v20, v17
	v_add_f32_e32 v11, v0, v1
	v_pk_mul_f32 v[0:1], v[8:9], v[42:43] op_sel_hi:[0,1]
	v_pk_mul_f32 v[0:1], v[0:1], v[12:13]
	v_mov_b32_e32 v16, v21
	v_pk_mul_f32 v[2:3], v[20:21], v[0:1]
	v_pk_mul_f32 v[0:1], v[16:17], v[0:1]
	v_sub_f32_e32 v5, v2, v3
	v_add_f32_e32 v12, v0, v1
	v_pk_mul_f32 v[0:1], v[8:9], v[40:41] op_sel_hi:[0,1]
	s_waitcnt vmcnt(3)
	v_mov_b32_e32 v2, v22
	s_waitcnt vmcnt(2)
	v_mov_b32_e32 v3, v26
	v_pk_mul_f32 v[0:1], v[0:1], v[2:3]
	s_waitcnt vmcnt(1)
	v_mov_b32_e32 v2, v50
	s_waitcnt vmcnt(0)
; __device__ __forceinline__ int v_st(int k, int c) { const int kk = (k & ~0xC) | ((k & 4) << 1) | ((k & 8) >> 1); return ((kk >> 3) * 4 + (c >> 5)) * 512 + ((kk & 7) * 32 + (c & 31)) * 2; }
; __device__ __forceinline__ int v_rd_base(int lane) { return ((lane & 3) << 3) | (((lane >> 2) & 3) << 6) | (((lane >> 4) & 1) << 5) | (((lane >> 5) & 1) << 8); }
; #define SLOAD(i, k0) do { sr_[i].vs0 = ld8(&Vh[(long)((k0) + sr) * LDK + sc]); sr_[i].vs1 = ld8(&Vh[(long)((k0) + 32 + sr) * LDK + sc]); \
;     sr_[i].ks0 = ld8(&Kh[(long)((k0) + sr) * LDK + sc]); sr_[i].ks1 = ld8(&Kh[(long)((k0) + 32 + sr) * LDK + sc]); } while (0)
; #define SWRITE(b, i) do { *(bf16x8*)(V_lds + (b) * SHM_V + vst0) = sr_[i].vs0;          \
;     *(bf16x8*)(V_lds + (b) * SHM_V + vst1) = sr_[i].vs1; int kc = sc * 2;               \
;     *(bf16x8*)(K_lds + (b) * SHM_K + KSWZ(sr, kc)) = sr_[i].ks0;                       \
;     *(bf16x8*)(K_lds + (b) * SHM_K + KSWZ(32 + sr, kc)) = sr_[i].ks1; } while (0)
; __device__ __forceinline__ void qkt(f32x16& p0, f32x16& p1, const char* Ks, const bf16x8* qr, int r32, int hi) {
;   p0 = f32x16{}; p1 = f32x16{};
;   for (int d0 = 0; d0 < 8; ++d0) { int cb = (d0 * 16 + hi * 8) * 2;
;     bf16x8 b0 = *reinterpret_cast<const bf16x8*>(Ks + KSWZ(r32, cb));
;     bf16x8 b1 = *reinterpret_cast<const bf16x8*>(Ks + KSWZ(32 + r32, cb));
;     p0 = __builtin_amdgcn_mfma_f32_32x32x16_bf16(b0, qr[d0], p0, 0, 0, 0);
;     p1 = __builtin_amdgcn_mfma_f32_32x32x16_bf16(b1, qr[d0], p1, 0, 0, 0); }
; __device__ __forceinline__ void attn_body(const bf16_t* Qb, const bf16_t* Kh, const bf16_t* Vh, const bf16_t* Gb, bf16_t* Ob, int seq, char* lds,
;                                           const float* qgain, const float* cosA, const float* sinA, int t0) {
;     ...
;   const int sr = tid >> 4, sc = (tid & 15) * 8, vst0 = v_st(sr, sc), vst1 = v_st(32 + sr, sc);
;   const int vb0 = (int)(uintptr_t)V_lds + v_rd_base(lane);
;   struct { bf16x8 vs0, vs1, ks0, ks1; } sr_[2];
;     ...
;   f32x16 pA0, pA1, pB0, pB1; float mnA, mnB, alA, alB; bf16x8 pa0, pa1, pa2, pa3; const int NT = seq / KVBLK;
;   constexpr int SE = 0, SO = 1;
;   SLOAD(SE, 0); asm volatile("s_waitcnt vmcnt(0)" ::: "memory"); SWRITE(0, SE); __syncthreads();
;   qkt(pA0, pA1, K_lds, qr, r32, hi); partialSM(pA0, pA1, m_reg, mnA, alA);
	v_mov_b32_e32 v3, v54
	v_pk_mul_f32 v[2:3], v[2:3], v[0:1]
	v_mov_b32_e32 v26, v23
	v_sub_f32_e32 v13, v2, v3
	v_mov_b32_e32 v2, v54
	v_mov_b32_e32 v3, v50
	v_pk_mul_f32 v[0:1], v[2:3], v[0:1]
	v_mov_b32_e32 v54, v51
	v_add_f32_e32 v14, v0, v1
	v_pk_mul_f32 v[0:1], v[8:9], v[36:37] op_sel_hi:[0,1]
	v_pk_mul_f32 v[0:1], v[0:1], v[26:27]
	v_mov_b32_e32 v50, v55
	v_pk_mul_f32 v[2:3], v[54:55], v[0:1]
	v_pk_mul_f32 v[0:1], v[50:51], v[0:1]
	v_sub_f32_e32 v15, v2, v3
	v_add_f32_e32 v16, v0, v1
	v_pk_mul_f32 v[0:1], v[8:9], v[34:35] op_sel_hi:[0,1]
	v_mov_b32_e32 v2, v24
	v_mov_b32_e32 v3, v28
	v_pk_mul_f32 v[0:1], v[0:1], v[2:3]
	v_mov_b32_e32 v2, v52
	v_mov_b32_e32 v3, v56
	v_pk_mul_f32 v[2:3], v[2:3], v[0:1]
	v_mov_b32_e32 v28, v25
	v_sub_f32_e32 v17, v2, v3
	v_mov_b32_e32 v2, v56
	v_mov_b32_e32 v3, v52
	v_pk_mul_f32 v[0:1], v[2:3], v[0:1]
	v_mov_b32_e32 v56, v53
	v_add_f32_e32 v18, v0, v1
	v_pk_mul_f32 v[0:1], v[8:9], v[32:33] op_sel_hi:[0,1]
	v_pk_mul_f32 v[0:1], v[0:1], v[28:29]
	v_mov_b32_e32 v52, v57
	v_pk_mul_f32 v[2:3], v[56:57], v[0:1]
	v_pk_mul_f32 v[0:1], v[52:53], v[0:1]
	v_sub_f32_e32 v2, v2, v3
	v_add_f32_e32 v0, v0, v1
	v_cvt_pk_bf16_f32 v124, v9, v7
	v_cvt_pk_bf16_f32 v125, v4, v5
	v_cvt_pk_bf16_f32 v126, v13, v15
	v_cvt_pk_bf16_f32 v127, v17, v2
	v_cvt_pk_bf16_f32 v120, v6, v10
	v_cvt_pk_bf16_f32 v121, v11, v12
	v_cvt_pk_bf16_f32 v122, v14, v16
	v_lshlrev_b32_e32 v16, 3, v94
	v_cvt_pk_bf16_f32 v123, v18, v0
	v_and_b32_e32 v180, 0x78, v16
	v_mad_i64_i32 v[0:1], s[22:23], v48, s69, 0
	v_or_b32_e32 v0, v0, v180
	v_add_u32_e32 v17, 32, v48
	v_lshlrev_b64 v[8:9], 1, v[0:1]
	v_lshl_add_u64 v[0:1], s[42:43], 0, v[8:9]
	v_mad_i64_i32 v[4:5], s[22:23], v17, s69, 0
	global_load_dwordx4 v[0:3], v[0:1], off
	v_or_b32_e32 v4, v4, v180
	v_lshlrev_b64 v[12:13], 1, v[4:5]
	v_lshl_add_u64 v[4:5], s[42:43], 0, v[12:13]
	v_lshl_add_u64 v[8:9], s[36:37], 0, v[8:9]
	global_load_dwordx4 v[4:7], v[4:5], off
	v_lshl_add_u64 v[12:13], s[36:37], 0, v[12:13]
	global_load_dwordx4 v[8:11], v[8:9], off
	v_and_b32_e32 v18, 0xfffff0, v48
	global_load_dwordx4 v[12:15], v[12:13], off
	v_lshlrev_b32_e32 v19, 1, v48
	v_and_or_b32 v18, v19, 8, v18
	v_lshrrev_b32_e32 v19, 1, v48
	v_lshrrev_b32_e32 v18, 1, v18
	v_bfe_u32 v16, v16, 5, 2
	v_and_b32_e32 v20, 3, v48
	v_or_b32_e32 v18, v18, v16
	v_and_or_b32 v19, v19, 4, v20
	v_lshlrev_b32_e32 v20, 1, v180
	v_and_b32_e32 v22, 0xfffff0, v17
	v_lshlrev_b32_e32 v23, 1, v17
	v_lshlrev_b32_e32 v18, 9, v18
	v_lshlrev_b32_e32 v19, 6, v19
	v_and_b32_e32 v21, 48, v20
	v_and_or_b32 v22, v23, 8, v22
	v_or3_b32 v18, v18, v19, v21
	v_lshrrev_b32_e32 v22, 1, v22
	v_or_b32_e32 v16, v22, v16
	v_add_u32_e32 v192, 0, v18
	v_lshlrev_b32_e32 v16, 9, v16
	s_waitcnt vmcnt(0)
	v_or3_b32 v16, v16, v19, v21
	v_add_u32_e32 v193, 0, v16
	v_or_b32_e32 v66, v66, v180
	v_lshlrev_b64 v[66:67], 1, v[66:67]
	v_or_b32_e32 v70, v70, v180
	v_lshl_add_u64 v[68:69], s[42:43], 0, v[66:67]
	v_lshlrev_b64 v[70:71], 1, v[70:71]
	v_lshl_add_u64 v[66:67], s[36:37], 0, v[66:67]
	v_lshl_add_u64 v[72:73], s[42:43], 0, v[70:71]
	s_waitcnt vmcnt(3)
	ds_write_b128 v192, v[0:3]
	v_lshlrev_b32_e32 v0, 8, v48
	v_and_b32_e32 v1, 0x70, v94
	v_bitop3_b32 v0, v20, v0, v1 bitop3:0xde
	v_add_u32_e32 v199, 0, v0
	v_lshlrev_b32_e32 v0, 8, v17
	s_waitcnt vmcnt(2)
	ds_write_b128 v193, v[4:7]
	s_waitcnt vmcnt(1)
	ds_write_b128 v199, v[8:11] offset:32768
	v_bitop3_b32 v0, v20, v0, v1 bitop3:0xde
	v_lshlrev_b32_e32 v8, 8, v181
	v_and_b32_e32 v9, 0x70, v185
	v_add_u32_e32 v200, 0, v0
	v_bitop3_b32 v0, v176, v8, v9 bitop3:0xde
	v_add_u32_e32 v201, 0, v0
	s_waitcnt vmcnt(0)
	ds_write_b128 v200, v[12:15] offset:32768
	s_waitcnt lgkmcnt(0)
	s_barrier
	ds_read_b128 v[0:3], v201 offset:32768
	ds_read_b128 v[4:7], v201 offset:40960
	s_waitcnt lgkmcnt(1)
	v_mfma_f32_32x32x16_bf16 v[32:47], v[0:3], v[100:103], 0
	v_or_b32_e32 v0, 32, v176
	v_bitop3_b32 v0, v0, v8, v9 bitop3:0xde
	v_add_u32_e32 v204, 0, v0
	v_lshlrev_b32_e32 v10, 3, v186
	s_waitcnt lgkmcnt(0)
	v_mfma_f32_32x32x16_bf16 v[16:31], v[4:7], v[100:103], 0
	ds_read_b128 v[0:3], v204 offset:32768
	ds_read_b128 v[4:7], v204 offset:40960
	s_waitcnt lgkmcnt(1)
	v_mfma_f32_32x32x16_bf16 v[32:47], v[0:3], v[108:111], v[32:47]
	v_or_b32_e32 v0, 64, v176
	v_bitop3_b32 v0, v0, v8, v9 bitop3:0xde
	v_add_u32_e32 v205, 0, v0
	s_waitcnt lgkmcnt(0)
	v_mfma_f32_32x32x16_bf16 v[16:31], v[4:7], v[108:111], v[16:31]
	ds_read_b128 v[0:3], v205 offset:32768
	ds_read_b128 v[4:7], v205 offset:40960
	s_waitcnt lgkmcnt(1)
	v_mfma_f32_32x32x16_bf16 v[32:47], v[0:3], v[96:99], v[32:47]
	v_or_b32_e32 v0, 0x60, v176
	v_bitop3_b32 v0, v0, v8, v9 bitop3:0xde
	v_add_u32_e32 v202, 0, v0
	s_waitcnt lgkmcnt(0)
	v_mfma_f32_32x32x16_bf16 v[16:31], v[4:7], v[96:99], v[16:31]
	ds_read_b128 v[0:3], v202 offset:32768
	ds_read_b128 v[4:7], v202 offset:40960
	s_waitcnt lgkmcnt(1)
	v_mfma_f32_32x32x16_bf16 v[32:47], v[0:3], v[104:107], v[32:47]
	v_or_b32_e32 v0, 0x80, v176
	v_bitop3_b32 v0, v0, v8, v9 bitop3:0xde
	v_add_u32_e32 v203, 0, v0
	s_waitcnt lgkmcnt(0)
	v_mfma_f32_32x32x16_bf16 v[16:31], v[4:7], v[104:107], v[16:31]
	ds_read_b128 v[0:3], v203 offset:32768
	ds_read_b128 v[4:7], v203 offset:40960
	s_waitcnt lgkmcnt(1)
	v_mfma_f32_32x32x16_bf16 v[32:47], v[0:3], v[116:119], v[32:47]
	v_or_b32_e32 v0, 0xa0, v176
	v_bitop3_b32 v0, v0, v8, v9 bitop3:0xde
	v_add_u32_e32 v206, 0, v0
	ds_read_b128 v[0:3], v206 offset:32768
	s_waitcnt lgkmcnt(1)
	v_mfma_f32_32x32x16_bf16 v[16:31], v[4:7], v[116:119], v[16:31]
	v_and_b32_e32 v4, 0x3fffffc0, v94
	v_lshl_add_u32 v187, v4, 2, s19
	v_and_b32_e32 v4, 0xc0, v185
	v_and_or_b32 v11, v10, 24, v4
	ds_read_b128 v[4:7], v206 offset:40960
	v_and_b32_e32 v10, 0x100, v10
	s_mov_b32 s19, -1
	s_waitcnt lgkmcnt(1)
; #define SLOAD(i, k0) do { sr_[i].vs0 = ld8(&Vh[(long)((k0) + sr) * LDK + sc]); sr_[i].vs1 = ld8(&Vh[(long)((k0) + 32 + sr) * LDK + sc]); \
;     sr_[i].ks0 = ld8(&Kh[(long)((k0) + sr) * LDK + sc]); sr_[i].ks1 = ld8(&Kh[(long)((k0) + 32 + sr) * LDK + sc]); } while (0)
; #define SWRITE(b, i) do { *(bf16x8*)(V_lds + (b) * SHM_V + vst0) = sr_[i].vs0;          \
;     *(bf16x8*)(V_lds + (b) * SHM_V + vst1) = sr_[i].vs1; int kc = sc * 2;               \
;     *(bf16x8*)(K_lds + (b) * SHM_K + KSWZ(sr, kc)) = sr_[i].ks0;                       \
;     *(bf16x8*)(K_lds + (b) * SHM_K + KSWZ(32 + sr, kc)) = sr_[i].ks1; } while (0)
; #define SWAIT() asm volatile("s_waitcnt vmcnt(4)" ::: "memory")
; __device__ __forceinline__ void partialSM(f32x16& p0, f32x16& p1, float& m_reg, float& mn, float& alpha) {
;   constexpr float C = SCALE * 1.4426950408889634f;
;   float pmax = p0[0]; for (int r = 1; r < 16; ++r) pmax = fmaxf(pmax, p0[r]); for (int r = 0; r < 16; ++r) pmax = fmaxf(pmax, p1[r]);
;   { auto rr = __builtin_amdgcn_permlane32_swap(__float_as_uint(pmax), __float_as_uint(pmax), false, false);
;     pmax = fmaxf(__uint_as_float(rr[0]), __uint_as_float(rr[1])); }
;   if (__builtin_expect(__all(pmax - m_reg <= THR / SCALE), 1)) { mn = m_reg; alpha = 1.f; }
;   else { mn = fmaxf(m_reg, pmax); alpha = __builtin_amdgcn_exp2f((m_reg - mn) * C); m_reg = mn; }
;   float mnC = -mn * C;
;   for (int r = 0; r < 16; ++r) p0[r] = fmaf(p0[r], C, mnC); for (int r = 0; r < 16; ++r) p1[r] = fmaf(p1[r], C, mnC);
;   for (int r = 0; r < 16; ++r) p0[r] = __builtin_amdgcn_exp2f(p0[r]);
; __device__ __forceinline__ void attn_body(const bf16_t* Qb, const bf16_t* Kh, const bf16_t* Vh, const bf16_t* Gb, bf16_t* Ob, int seq, char* lds,
;                                           const float* qgain, const float* cosA, const float* sinA, int t0) {
;     ...
;   f32x16 pA0, pA1, pB0, pB1; float mnA, mnB, alA, alB; bf16x8 pa0, pa1, pa2, pa3; const int NT = seq / KVBLK;
;   constexpr int SE = 0, SO = 1;
;   SLOAD(SE, 0); asm volatile("s_waitcnt vmcnt(0)" ::: "memory"); SWRITE(0, SE); __syncthreads();
;   qkt(pA0, pA1, K_lds, qr, r32, hi); partialSM(pA0, pA1, m_reg, mnA, alA);
;   SLOAD(SO, KVBLK); if (2 < NT) SLOAD(SE, 2 * KVBLK);
;   SWAIT(); SWRITE(1, SO); __syncthreads();
	v_mfma_f32_32x32x16_bf16 v[32:47], v[0:3], v[124:127], v[32:47]
	v_lshlrev_b32_e32 v0, 1, v94
	v_and_b32_e32 v12, 32, v0
	v_or_b32_e32 v0, 0xc0, v176
	v_bitop3_b32 v0, v0, v8, v9 bitop3:0xde
	v_add_u32_e32 v207, 0, v0
	ds_read_b128 v[0:3], v207 offset:32768
	v_or3_b32 v74, v11, v12, v10
	s_waitcnt lgkmcnt(1)
	v_mfma_f32_32x32x16_bf16 v[16:31], v[4:7], v[124:127], v[16:31]
	ds_read_b128 v[4:7], v207 offset:40960
	v_add_u32_e32 v191, s21, v74
	v_lshl_add_u32 v188, v181, 2, v187
	s_waitcnt lgkmcnt(1)
	v_mfma_f32_32x32x16_bf16 v[32:47], v[0:3], v[112:115], v[32:47]
	v_or_b32_e32 v0, 0xe0, v176
	v_bitop3_b32 v0, v0, v8, v9 bitop3:0xde
	v_add_u32_e32 v208, 0, v0
	ds_read_b128 v[0:3], v208 offset:32768
	ds_read_b128 v[50:53], v208 offset:40960
	s_waitcnt lgkmcnt(2)
	v_mfma_f32_32x32x16_bf16 v[16:31], v[4:7], v[112:115], v[16:31]
	s_waitcnt lgkmcnt(1)
	v_mfma_f32_32x32x16_bf16 v[32:47], v[0:3], v[120:123], v[32:47]
	v_mov_b64_e32 v[0:1], s[72:73]
	v_mov_b64_e32 v[2:3], s[74:75]
	v_mov_b64_e32 v[4:5], s[76:77]
	v_mov_b64_e32 v[6:7], s[78:79]
	v_mov_b64_e32 v[8:9], s[80:81]
	v_mov_b64_e32 v[10:11], s[82:83]
	v_mov_b64_e32 v[12:13], s[84:85]
	s_waitcnt lgkmcnt(0)
	v_mfma_f32_32x32x16_bf16 v[16:31], v[50:53], v[120:123], v[16:31]
	s_nop 2
	v_max_f32_e32 v50, v33, v33
	v_max_f32_e32 v51, v32, v32
	v_max_f32_e32 v50, v51, v50
	v_max3_f32 v50, v50, v34, v35
	v_max3_f32 v50, v50, v36, v37
	v_max3_f32 v50, v50, v38, v39
	v_max3_f32 v50, v50, v40, v41
	v_max3_f32 v50, v50, v42, v43
	v_max3_f32 v50, v50, v44, v45
	v_max3_f32 v50, v50, v46, v47
	v_max3_f32 v50, v50, v16, v17
	v_max3_f32 v50, v50, v18, v19
	v_max3_f32 v50, v50, v20, v21
	v_max3_f32 v50, v50, v22, v23
	v_max3_f32 v50, v50, v24, v25
	v_max3_f32 v50, v50, v26, v27
	v_max3_f32 v50, v50, v28, v29
	v_max3_f32 v75, v50, v30, v31
	v_add_u32_e32 v50, 64, v48
	v_add_u32_e32 v52, 0x60, v48
	v_mad_i64_i32 v[50:51], s[22:23], v50, s69, 0
	v_mad_i64_i32 v[52:53], s[22:23], v52, s69, 0
	v_or_b32_e32 v50, v50, v180
	v_or_b32_e32 v52, v52, v180
	v_lshlrev_b64 v[58:59], 1, v[50:51]
	v_lshlrev_b64 v[60:61], 1, v[52:53]
	v_lshl_add_u64 v[50:51], s[42:43], 0, v[58:59]
	v_lshl_add_u64 v[54:55], s[42:43], 0, v[60:61]
	v_lshl_add_u64 v[58:59], s[36:37], 0, v[58:59]
	v_lshl_add_u64 v[62:63], s[36:37], 0, v[60:61]
	global_load_dwordx4 v[50:53], v[50:51], off
	s_nop 0
	global_load_dwordx4 v[54:57], v[54:55], off
	s_nop 0
	global_load_dwordx4 v[58:61], v[58:59], off
	s_nop 0
	global_load_dwordx4 v[62:65], v[62:63], off
	s_nop 0
	global_load_dwordx4 v[128:131], v[68:69], off
	global_load_dwordx4 v[132:135], v[72:73], off
	v_lshl_add_u64 v[68:69], s[36:37], 0, v[70:71]
	global_load_dwordx4 v[240:243], v[66:67], off
	global_load_dwordx4 v[246:249], v[68:69], off
	v_add_co_u32_e32 v66, vcc, 0xa0000, v66
	s_nop 1
	v_addc_co_u32_e32 v67, vcc, 0, v67, vcc
	v_add_co_u32_e32 v68, vcc, 0xa0000, v68
	s_nop 1
	v_addc_co_u32_e32 v69, vcc, 0, v69, vcc
	global_load_dwordx4 v[136:139], v[66:67], off
	global_load_dwordx4 v[140:143], v[68:69], off
	v_mov_b32_e32 v76, v75
	s_nop 1
	v_permlane32_swap_b32_e32 v75, v76
	v_max_f32_e32 v66, v76, v76
	v_max_f32_e32 v67, v75, v75
	v_max_f32_e32 v66, v67, v66
	v_add_f32_e32 v67, 0x7149f2ca, v66
	v_max_f32_e32 v66, 0xf149f2ca, v66
	v_cmp_ge_f32_e32 vcc, s71, v67
	v_sub_f32_e32 v67, 0xf149f2ca, v66
	v_mul_f32_e32 v67, 0x3e0293ee, v67
	v_exp_f32_e32 v67, v67
	s_cmp_eq_u64 vcc, exec
	s_cselect_b64 vcc, -1, 0
	v_mov_b32_e32 v68, 0xf149f2ca
	v_cndmask_b32_e32 v164, v66, v68, vcc
	v_mul_f32_e32 v66, 0xbe0293ee, v164
	v_cndmask_b32_e64 v209, v67, 1.0, vcc
	v_mov_b32_e32 v67, v66
	v_fmac_f32_e32 v67, 0x3e0293ee, v47
	v_mov_b64_e32 v[14:15], s[86:87]
	s_movk_i32 s72, 0x2800
	v_pk_fma_f32 v[156:157], v[16:17], s[62:63], v[66:67] op_sel_hi:[1,0,0]
	v_lshl_add_u64 v[16:17], v[48:49], 0, s[38:39]
	v_fmamk_f32 v32, v32, 0x3e0293ee, v66
	v_fmamk_f32 v33, v33, 0x3e0293ee, v66
	v_fmamk_f32 v34, v34, 0x3e0293ee, v66
	v_fmamk_f32 v35, v35, 0x3e0293ee, v66
	v_fmamk_f32 v36, v36, 0x3e0293ee, v66
	v_fmamk_f32 v37, v37, 0x3e0293ee, v66
	v_fmamk_f32 v38, v38, 0x3e0293ee, v66
	v_fmamk_f32 v39, v39, 0x3e0293ee, v66
	v_fmamk_f32 v40, v40, 0x3e0293ee, v66
	v_fmamk_f32 v41, v41, 0x3e0293ee, v66
	v_fmamk_f32 v42, v42, 0x3e0293ee, v66
	v_fmamk_f32 v43, v43, 0x3e0293ee, v66
	v_fmamk_f32 v44, v44, 0x3e0293ee, v66
	v_fmamk_f32 v45, v45, 0x3e0293ee, v66
	v_fmamk_f32 v46, v46, 0x3e0293ee, v66
	v_pk_fma_f32 v[154:155], v[18:19], s[62:63], v[66:67] op_sel_hi:[1,0,0]
	v_mad_u64_u32 v[18:19], s[22:23], v16, s72, 0
	v_and_b32_e32 v16, 15, v94
	v_exp_f32_e32 v175, v32
	v_exp_f32_e32 v216, v33
	v_exp_f32_e32 v161, v34
	v_exp_f32_e32 v213, v35
	v_exp_f32_e32 v162, v36
	v_exp_f32_e32 v174, v37
	v_exp_f32_e32 v163, v38
	v_exp_f32_e32 v173, v39
	v_exp_f32_e32 v170, v40
	v_exp_f32_e32 v172, v41
	v_exp_f32_e32 v169, v42
	v_exp_f32_e32 v171, v43
	v_exp_f32_e32 v166, v44
	v_exp_f32_e32 v168, v45
	v_exp_f32_e32 v165, v46
	v_exp_f32_e32 v167, v67
	v_lshlrev_b32_e32 v16, 4, v16
	s_waitcnt vmcnt(4)
	v_mad_i32_i24 v17, v17, s72, v19
	v_or3_b32 v16, v18, s20, v16
	v_pk_fma_f32 v[150:151], v[30:31], s[62:63], v[66:67] op_sel_hi:[1,0,0]
	v_pk_fma_f32 v[152:153], v[28:29], s[62:63], v[66:67] op_sel_hi:[1,0,0]
	v_pk_fma_f32 v[158:159], v[26:27], s[62:63], v[66:67] op_sel_hi:[1,0,0]
	v_pk_fma_f32 v[144:145], v[24:25], s[62:63], v[66:67] op_sel_hi:[1,0,0]
	v_pk_fma_f32 v[146:147], v[22:23], s[62:63], v[66:67] op_sel_hi:[1,0,0]
	v_pk_fma_f32 v[148:149], v[20:21], s[62:63], v[66:67] op_sel_hi:[1,0,0]
	s_waitcnt vmcnt(7)
	ds_write_b128 v192, v[50:53] offset:16384
	s_waitcnt vmcnt(6)
	ds_write_b128 v193, v[54:57] offset:16384
	s_waitcnt vmcnt(5)
	ds_write_b128 v199, v[58:61] offset:49152
	s_waitcnt vmcnt(4)
	ds_write_b128 v200, v[62:65] offset:49152
	s_addk_i32 s21, 0x4000
	v_lshl_add_u64 v[182:183], s[50:51], 0, v[16:17]
	v_mov_b64_e32 v[62:63], v[14:15]
	v_mov_b64_e32 v[46:47], v[14:15]
	v_mov_b64_e32 v[30:31], v[14:15]
	v_cmp_gt_u32_e64 s[36:37], 32, v186
	v_add_u32_e32 v190, s21, v74
	v_mov_b64_e32 v[60:61], v[12:13]
	v_mov_b64_e32 v[58:59], v[10:11]
	v_mov_b64_e32 v[56:57], v[8:9]
	v_mov_b64_e32 v[54:55], v[6:7]
	v_mov_b64_e32 v[52:53], v[4:5]
	v_mov_b64_e32 v[50:51], v[2:3]
	v_mov_b64_e32 v[48:49], v[0:1]
	v_mov_b64_e32 v[44:45], v[12:13]
	v_mov_b64_e32 v[42:43], v[10:11]
	v_mov_b64_e32 v[40:41], v[8:9]
	v_mov_b64_e32 v[38:39], v[6:7]
	v_mov_b64_e32 v[36:37], v[4:5]
	v_mov_b64_e32 v[34:35], v[2:3]
	v_mov_b64_e32 v[32:33], v[0:1]
	v_mov_b64_e32 v[28:29], v[12:13]
	v_mov_b64_e32 v[26:27], v[10:11]
	v_mov_b64_e32 v[24:25], v[8:9]
	v_mov_b64_e32 v[22:23], v[6:7]
	v_mov_b64_e32 v[20:21], v[4:5]
	v_mov_b64_e32 v[18:19], v[2:3]
	v_mov_b64_e32 v[16:17], v[0:1]
	s_waitcnt lgkmcnt(0)
	s_barrier
; __device__ __forceinline__ void finishSM(f32x16& p0, f32x16& p1, float alpha, float& l_reg, bf16x8& pa0, bf16x8& pa1, bf16x8& pa2, bf16x8& pa3) {
;   for (int r = 0; r < 16; ++r) p1[r] = __builtin_amdgcn_exp2f(p1[r]);
;   float ps = 0; for (int r = 0; r < 16; ++r) ps += p0[r]; for (int r = 0; r < 16; ++r) ps += p1[r];
;   { auto rr = __builtin_amdgcn_permlane32_swap(__float_as_uint(ps), __float_as_uint(ps), false, false);
;     ps = __uint_as_float(rr[0]) + __uint_as_float(rr[1]); }
;   l_reg = l_reg * alpha + ps;
;     ...
;   PK4(p0, 0, pa0); PK4(p0, 8, pa1); PK4(p1, 0, pa2); PK4(p1, 8, pa3);
; __device__ __forceinline__ void qkt(f32x16& p0, f32x16& p1, const char* Ks, const bf16x8* qr, int r32, int hi) {
;   p0 = f32x16{}; p1 = f32x16{};
;   for (int d0 = 0; d0 < 8; ++d0) { int cb = (d0 * 16 + hi * 8) * 2;
;     bf16x8 b0 = *reinterpret_cast<const bf16x8*>(Ks + KSWZ(r32, cb));
;     bf16x8 b1 = *reinterpret_cast<const bf16x8*>(Ks + KSWZ(32 + r32, cb));
;     p0 = __builtin_amdgcn_mfma_f32_32x32x16_bf16(b0, qr[d0], p0, 0, 0, 0);
;     p1 = __builtin_amdgcn_mfma_f32_32x32x16_bf16(b1, qr[d0], p1, 0, 0, 0); }
	s_waitcnt vmcnt(2)
	ds_write_b128 v199, v[240:243] offset:32768
	ds_write_b128 v200, v[246:249] offset:32768
	ds_read_b128 v[64:67], v201 offset:49152
	ds_read_b128 v[68:71], v201 offset:57344
	ds_read_b128 v[218:221], v204 offset:49152
	ds_read_b128 v[222:225], v204 offset:57344
	ds_read_b128 v[240:243], v205 offset:49152
	ds_read_b128 v[246:249], v205 offset:57344
.LBB0_259:
	v_add_f32_e32 v160, v216, v175
	s_waitcnt lgkmcnt(5)
	v_mfma_f32_32x32x16_bf16 v[80:95], v[64:67], v[100:103], 0
	v_add_f32_e32 v160, v161, v160
	v_add_f32_e32 v160, v213, v160
	v_add_f32_e32 v160, v162, v160
	v_add_f32_e32 v160, v174, v160
	v_add_f32_e32 v160, v163, v160
	v_add_f32_e32 v160, v173, v160
	v_add_f32_e32 v160, v170, v160
	s_waitcnt lgkmcnt(4)
	v_mfma_f32_32x32x16_bf16 v[64:79], v[68:71], v[100:103], 0
	v_add_f32_e32 v160, v172, v160
	v_add_f32_e32 v160, v169, v160
	v_add_f32_e32 v160, v171, v160
	v_exp_f32_e32 v156, v156
	v_add_f32_e32 v160, v166, v160
	v_exp_f32_e32 v157, v157
	v_add_f32_e32 v160, v168, v160
	s_waitcnt lgkmcnt(3)
	v_mfma_f32_32x32x16_bf16 v[80:95], v[218:221], v[108:111], v[80:95]
	v_exp_f32_e32 v154, v154
	v_add_f32_e32 v160, v165, v160
	v_exp_f32_e32 v155, v155
	v_add_f32_e32 v160, v167, v160
	v_exp_f32_e32 v148, v148
	v_add_f32_e32 v160, v156, v160
	v_exp_f32_e32 v149, v149
	s_waitcnt lgkmcnt(2)
	v_mfma_f32_32x32x16_bf16 v[64:79], v[222:225], v[108:111], v[64:79]
	ds_read_b128 v[218:221], v202 offset:49152
	ds_read_b128 v[222:225], v202 offset:57344
	v_add_f32_e32 v160, v157, v160
	v_exp_f32_e32 v146, v146
	v_add_f32_e32 v160, v154, v160
	v_exp_f32_e32 v147, v147
	v_add_f32_e32 v160, v155, v160
	v_exp_f32_e32 v144, v144
	s_waitcnt lgkmcnt(3)
	v_mfma_f32_32x32x16_bf16 v[80:95], v[240:243], v[96:99], v[80:95]
	v_add_f32_e32 v160, v148, v160
	v_exp_f32_e32 v145, v145
	v_add_f32_e32 v160, v149, v160
	v_exp_f32_e32 v158, v158
	v_add_f32_e32 v160, v146, v160
	v_exp_f32_e32 v159, v159
	v_add_f32_e32 v160, v147, v160
	s_waitcnt lgkmcnt(2)
	v_mfma_f32_32x32x16_bf16 v[64:79], v[246:249], v[96:99], v[64:79]
	ds_read_b128 v[240:243], v203 offset:49152
	ds_read_b128 v[246:249], v203 offset:57344
	v_exp_f32_e32 v152, v152
	v_add_f32_e32 v160, v144, v160
	v_exp_f32_e32 v153, v153
	v_add_f32_e32 v160, v145, v160
	v_exp_f32_e32 v150, v150
	v_add_f32_e32 v160, v158, v160
	s_waitcnt lgkmcnt(3)
	v_mfma_f32_32x32x16_bf16 v[80:95], v[218:221], v[104:107], v[80:95]
	v_exp_f32_e32 v151, v151
	v_add_f32_e32 v160, v159, v160
	v_add_f32_e32 v160, v152, v160
	v_add_f32_e32 v160, v153, v160
	v_add_f32_e32 v160, v150, v160
	v_add_f32_e32 v210, v151, v160
	v_mov_b32_e32 v211, v210
	s_waitcnt lgkmcnt(2)
	v_mfma_f32_32x32x16_bf16 v[64:79], v[222:225], v[104:107], v[64:79]
	ds_read_b128 v[218:221], v206 offset:49152
	ds_read_b128 v[222:225], v206 offset:57344
	v_permlane32_swap_b32_e32 v210, v211
	s_waitcnt lgkmcnt(3)
	v_mfma_f32_32x32x16_bf16 v[80:95], v[240:243], v[116:119], v[80:95]
	s_waitcnt lgkmcnt(2)
	v_mfma_f32_32x32x16_bf16 v[64:79], v[246:249], v[116:119], v[64:79]
	ds_read_b128 v[240:243], v207 offset:49152
	ds_read_b128 v[246:249], v207 offset:57344
	s_waitcnt lgkmcnt(3)
	v_mfma_f32_32x32x16_bf16 v[80:95], v[218:221], v[124:127], v[80:95]
	s_waitcnt lgkmcnt(2)
	v_mfma_f32_32x32x16_bf16 v[64:79], v[222:225], v[124:127], v[64:79]
	ds_read_b128 v[218:221], v208 offset:49152
	ds_read_b128 v[222:225], v208 offset:57344
	s_waitcnt lgkmcnt(3)
	v_mfma_f32_32x32x16_bf16 v[80:95], v[240:243], v[112:115], v[80:95]
	s_waitcnt lgkmcnt(2)
	v_mfma_f32_32x32x16_bf16 v[64:79], v[246:249], v[112:115], v[64:79]
	v_cvt_pk_bf16_f32 v160, v175, v216
	v_cvt_pk_bf16_f32 v161, v161, v213
	v_cvt_pk_bf16_f32 v162, v162, v174
	v_cvt_pk_bf16_f32 v163, v163, v173
	v_cvt_pk_bf16_f32 v170, v170, v172
	v_cvt_pk_bf16_f32 v171, v169, v171
	s_waitcnt lgkmcnt(1)
	v_mfma_f32_32x32x16_bf16 v[80:95], v[218:221], v[120:123], v[80:95]
	v_cvt_pk_bf16_f32 v172, v166, v168
	v_cvt_pk_bf16_f32 v173, v165, v167
	v_cvt_pk_bf16_f32 v166, v156, v157
	v_cvt_pk_bf16_f32 v167, v154, v155
	v_cvt_pk_bf16_f32 v168, v148, v149
	v_cvt_pk_bf16_f32 v169, v146, v147
	v_cvt_pk_bf16_f32 v212, v144, v145
	s_waitcnt lgkmcnt(0)
	v_mfma_f32_32x32x16_bf16 v[64:79], v[222:225], v[120:123], v[64:79]
	v_cvt_pk_bf16_f32 v213, v158, v159
	v_cvt_pk_bf16_f32 v214, v152, v153
	v_permlane32_swap_b32_e32 v160, v162
	v_cvt_pk_bf16_f32 v215, v150, v151
	v_permlane32_swap_b32_e32 v212, v214
	v_permlane32_swap_b32_e32 v161, v163
	v_permlane32_swap_b32_e32 v170, v172
	v_permlane32_swap_b32_e32 v171, v173
	v_permlane32_swap_b32_e32 v166, v168
	v_permlane32_swap_b32_e32 v167, v169
	v_permlane32_swap_b32_e32 v213, v215
	s_mov_b32 s20, 0xfff10000
	s_mov_b32 s21, -1
	v_lshl_add_u64 v[148:149], v[182:183], 0, s[20:21]
	s_mov_b32 s20, 0xfff60000
	v_lshl_add_u64 v[152:153], v[182:183], 0, s[20:21]
	s_mov_b32 s20, 0xfffb0000
	v_lshl_add_u64 v[250:251], v[182:183], 0, s[20:21]
	global_load_dwordx4 v[144:147], v[148:149], off
	global_load_dwordx4 v[148:151], v[250:251], off offset:-1024
	global_load_dwordx4 v[156:159], v[152:153], off
	global_load_dwordx4 v[152:155], v[182:183], off offset:-1024
	ds_read_b64_tr_b16 v[216:217], v191 offset:0
	ds_read_b64_tr_b16 v[218:219], v191 offset:0x800
	ds_read_b64_tr_b16 v[220:221], v191 offset:0x1000
	ds_read_b64_tr_b16 v[222:223], v191 offset:0x1800
	ds_read_b64_tr_b16 v[224:225], v191 offset:0x2000
	ds_read_b64_tr_b16 v[226:227], v191 offset:0x2800
	ds_read_b64_tr_b16 v[228:229], v191 offset:0x3000
	ds_read_b64_tr_b16 v[230:231], v191 offset:0x3800
	s_waitcnt lgkmcnt(0)
; #define SBAR() __builtin_amdgcn_sched_barrier(0)
; __device__ __forceinline__ void partialSM(f32x16& p0, f32x16& p1, float& m_reg, float& mn, float& alpha) {
;   constexpr float C = SCALE * 1.4426950408889634f;
;   float pmax = p0[0]; for (int r = 1; r < 16; ++r) pmax = fmaxf(pmax, p0[r]); for (int r = 0; r < 16; ++r) pmax = fmaxf(pmax, p1[r]);
;   { auto rr = __builtin_amdgcn_permlane32_swap(__float_as_uint(pmax), __float_as_uint(pmax), false, false);
;     pmax = fmaxf(__uint_as_float(rr[0]), __uint_as_float(rr[1])); }
;   if (__builtin_expect(__all(pmax - m_reg <= THR / SCALE), 1)) { mn = m_reg; alpha = 1.f; }
;   else { mn = fmaxf(m_reg, pmax); alpha = __builtin_amdgcn_exp2f((m_reg - mn) * C); m_reg = mn; }
; template <int D0> __device__ __forceinline__ void pv_one(f32x16& od, int vb, bf16x8 pa0, bf16x8 pa1, bf16x8 pa2, bf16x8 pa3) {
;   const s16x4 l0 = tr_read<v_rd_off(D0, 0, 0)>(vb), h0 = tr_read<v_rd_off(D0, 0, 1)>(vb), l1 = tr_read<v_rd_off(D0, 1, 0)>(vb), h1 = tr_read<v_rd_off(D0, 1, 1)>(vb);
;   const s16x4 l2 = tr_read<v_rd_off(D0, 2, 0)>(vb), h2 = tr_read<v_rd_off(D0, 2, 1)>(vb), l3 = tr_read<v_rd_off(D0, 3, 0)>(vb), h3 = tr_read<v_rd_off(D0, 3, 1)>(vb);
;   asm volatile("s_waitcnt lgkmcnt(0)" ::: "memory"); SBAR();
;     ...
;   od = __builtin_amdgcn_mfma_f32_32x32x16_bf16(pa0, PK(l0, h0), od, 0, 0, 0);
;   od = __builtin_amdgcn_mfma_f32_32x32x16_bf16(pa1, PK(l1, h1), od, 0, 0, 0);
;   od = __builtin_amdgcn_mfma_f32_32x32x16_bf16(pa2, PK(l2, h2), od, 0, 0, 0);
;   od = __builtin_amdgcn_mfma_f32_32x32x16_bf16(pa3, PK(l3, h3), od, 0, 0, 0);
;     ...
; }
; __device__ __forceinline__ void pv_d0(f32x16* o, int vb, bf16x8 pa0, bf16x8 pa1, bf16x8 pa2, bf16x8 pa3) {
;   pv_one<0>(o[0], vb, pa0, pa1, pa2, pa3); pv_one<1>(o[1], vb, pa0, pa1, pa2, pa3); pv_one<2>(o[2], vb, pa0, pa1, pa2, pa3); pv_one<3>(o[3], vb, pa0, pa1, pa2, pa3);
	s_nop 0
	v_mfma_f32_32x32x16_bf16 v[0:15], v[160:163], v[216:219], v[0:15]
	ds_read_b64_tr_b16 v[216:217], v191 offset:0x200
	ds_read_b64_tr_b16 v[218:219], v191 offset:0xa00
	v_mfma_f32_32x32x16_bf16 v[0:15], v[170:173], v[220:223], v[0:15]
	ds_read_b64_tr_b16 v[220:221], v191 offset:0x1200
	ds_read_b64_tr_b16 v[222:223], v191 offset:0x1a00
	v_mfma_f32_32x32x16_bf16 v[0:15], v[166:169], v[224:227], v[0:15]
	ds_read_b64_tr_b16 v[224:225], v191 offset:0x2200
	ds_read_b64_tr_b16 v[226:227], v191 offset:0x2a00
	v_mfma_f32_32x32x16_bf16 v[0:15], v[212:215], v[228:231], v[0:15]
	ds_read_b64_tr_b16 v[228:229], v191 offset:0x3200
	ds_read_b64_tr_b16 v[230:231], v191 offset:0x3a00
	s_waitcnt lgkmcnt(0)
	v_mfma_f32_32x32x16_bf16 v[48:63], v[160:163], v[216:219], v[48:63]
	ds_read_b64_tr_b16 v[216:217], v191 offset:0x400
	ds_read_b64_tr_b16 v[218:219], v191 offset:0xc00
	v_mfma_f32_32x32x16_bf16 v[48:63], v[170:173], v[220:223], v[48:63]
	ds_read_b64_tr_b16 v[220:221], v191 offset:0x1400
	ds_read_b64_tr_b16 v[222:223], v191 offset:0x1c00
	v_mfma_f32_32x32x16_bf16 v[48:63], v[166:169], v[224:227], v[48:63]
	ds_read_b64_tr_b16 v[224:225], v191 offset:0x2400
	ds_read_b64_tr_b16 v[226:227], v191 offset:0x2c00
	v_mfma_f32_32x32x16_bf16 v[48:63], v[212:215], v[228:231], v[48:63]
	ds_read_b64_tr_b16 v[228:229], v191 offset:0x3400
	ds_read_b64_tr_b16 v[230:231], v191 offset:0x3c00
	s_waitcnt lgkmcnt(0)
	v_mfma_f32_32x32x16_bf16 v[32:47], v[160:163], v[216:219], v[32:47]
	ds_read_b64_tr_b16 v[216:217], v191 offset:0x600
	ds_read_b64_tr_b16 v[218:219], v191 offset:0xe00
	v_mfma_f32_32x32x16_bf16 v[32:47], v[170:173], v[220:223], v[32:47]
	ds_read_b64_tr_b16 v[220:221], v191 offset:0x1600
	ds_read_b64_tr_b16 v[222:223], v191 offset:0x1e00
	v_mfma_f32_32x32x16_bf16 v[32:47], v[166:169], v[224:227], v[32:47]
	ds_read_b64_tr_b16 v[224:225], v191 offset:0x2600
	ds_read_b64_tr_b16 v[226:227], v191 offset:0x2e00
	v_mfma_f32_32x32x16_bf16 v[32:47], v[212:215], v[228:231], v[32:47]
	ds_read_b64_tr_b16 v[228:229], v191 offset:0x3600
	ds_read_b64_tr_b16 v[230:231], v191 offset:0x3e00
	s_waitcnt lgkmcnt(0)
	v_mfma_f32_32x32x16_bf16 v[16:31], v[160:163], v[216:219], v[16:31]
	v_max_f32_e32 v160, v80, v81
	v_max3_f32 v160, v160, v82, v83
	v_max3_f32 v160, v160, v84, v85
	v_max3_f32 v160, v160, v86, v87
	v_max3_f32 v160, v160, v88, v89
	v_max3_f32 v160, v160, v90, v91
	v_max3_f32 v160, v160, v92, v93
	v_mfma_f32_32x32x16_bf16 v[16:31], v[170:173], v[220:223], v[16:31]
	v_max3_f32 v160, v160, v94, v95
	v_max3_f32 v160, v160, v64, v65
	v_max3_f32 v160, v160, v66, v67
	v_max3_f32 v160, v160, v68, v69
	v_max3_f32 v160, v160, v70, v71
	v_max3_f32 v160, v160, v72, v73
	v_max3_f32 v160, v160, v74, v75
	v_max3_f32 v160, v160, v76, v77
	v_mfma_f32_32x32x16_bf16 v[16:31], v[166:169], v[224:227], v[16:31]
	v_max3_f32 v160, v160, v78, v79
	v_mov_b32_e32 v161, v160
	s_nop 1
	v_permlane32_swap_b32_e32 v160, v161
	v_max_f32_e32 v160, v160, v161
	v_sub_f32_e32 v161, v160, v164
	v_cmp_ge_f32_e32 vcc, s71, v161
	v_max_f32_e32 v160, v164, v160
	v_mfma_f32_32x32x16_bf16 v[16:31], v[212:215], v[228:231], v[16:31]
	v_sub_f32_e32 v161, v164, v160
	v_mul_f32_e32 v161, 0x3e0293ee, v161
	v_exp_f32_e32 v161, v161
	s_cmp_eq_u64 vcc, exec
	s_cselect_b64 s[38:39], -1, 0
	s_barrier
	s_waitcnt vmcnt(4)
	v_cndmask_b32_e64 v212, v161, 1.0, s[38:39]
	v_cmp_gt_f32_e32 vcc, 1.0, v212
	s_waitcnt vmcnt(7)
	ds_write_b128 v192, v[128:131]
	s_waitcnt vmcnt(6)
	ds_write_b128 v193, v[132:135]
	s_waitcnt vmcnt(5)
	ds_write_b128 v199, v[136:139] offset:49152
	s_waitcnt vmcnt(4)
	ds_write_b128 v200, v[140:143] offset:49152
	s_cbranch_vccz .LBB0_263
	s_and_saveexec_b64 s[42:43], s[36:37]
	ds_write_b32 v188, v212 offset:128
	s_or_b64 exec, exec, s[42:43]
	s_waitcnt lgkmcnt(0)
	v_add_u32_e32 v161, v187, v176
	ds_read_b128 v[166:169], v161 offset:224
	ds_read_b128 v[170:173], v161 offset:192
	ds_read_b128 v[214:217], v161 offset:160
	ds_read_b128 v[218:221], v161 offset:128
	s_waitcnt lgkmcnt(3)
	v_pk_mul_f32 v[12:13], v[12:13], v[166:167]
	s_waitcnt lgkmcnt(2)
	v_pk_mul_f32 v[8:9], v[8:9], v[170:171]
	s_waitcnt lgkmcnt(1)
	v_pk_mul_f32 v[4:5], v[4:5], v[214:215]
	v_pk_mul_f32 v[14:15], v[14:15], v[168:169]
	v_pk_mul_f32 v[10:11], v[10:11], v[172:173]
	v_pk_mul_f32 v[6:7], v[6:7], v[216:217]
	s_waitcnt lgkmcnt(0)
	v_pk_mul_f32 v[2:3], v[2:3], v[220:221]
	v_pk_mul_f32 v[0:1], v[0:1], v[218:219]
	v_pk_mul_f32 v[60:61], v[60:61], v[166:167]
	v_pk_mul_f32 v[56:57], v[56:57], v[170:171]
	v_pk_mul_f32 v[52:53], v[52:53], v[214:215]
	v_pk_mul_f32 v[62:63], v[62:63], v[168:169]
	v_pk_mul_f32 v[58:59], v[58:59], v[172:173]
	v_pk_mul_f32 v[54:55], v[54:55], v[216:217]
	v_pk_mul_f32 v[50:51], v[50:51], v[220:221]
	v_pk_mul_f32 v[48:49], v[48:49], v[218:219]
	v_pk_mul_f32 v[44:45], v[44:45], v[166:167]
	v_pk_mul_f32 v[40:41], v[40:41], v[170:171]
	v_pk_mul_f32 v[36:37], v[36:37], v[214:215]
	v_pk_mul_f32 v[46:47], v[46:47], v[168:169]
	v_pk_mul_f32 v[42:43], v[42:43], v[172:173]
	v_pk_mul_f32 v[38:39], v[38:39], v[216:217]
	v_pk_mul_f32 v[34:35], v[34:35], v[220:221]
	v_pk_mul_f32 v[32:33], v[32:33], v[218:219]
	v_pk_mul_f32 v[28:29], v[28:29], v[166:167]
	v_pk_mul_f32 v[24:25], v[24:25], v[170:171]
	v_pk_mul_f32 v[20:21], v[20:21], v[214:215]
	v_pk_mul_f32 v[30:31], v[30:31], v[168:169]
	v_pk_mul_f32 v[26:27], v[26:27], v[172:173]
	v_pk_mul_f32 v[22:23], v[22:23], v[216:217]
	v_pk_mul_f32 v[18:19], v[18:19], v[220:221]
	v_pk_mul_f32 v[16:17], v[16:17], v[218:219]
; __device__ __forceinline__ void partialSM(f32x16& p0, f32x16& p1, float& m_reg, float& mn, float& alpha) {
;   constexpr float C = SCALE * 1.4426950408889634f;
;   float pmax = p0[0]; for (int r = 1; r < 16; ++r) pmax = fmaxf(pmax, p0[r]); for (int r = 0; r < 16; ++r) pmax = fmaxf(pmax, p1[r]);
;   { auto rr = __builtin_amdgcn_permlane32_swap(__float_as_uint(pmax), __float_as_uint(pmax), false, false);
;     pmax = fmaxf(__uint_as_float(rr[0]), __uint_as_float(rr[1])); }
;   if (__builtin_expect(__all(pmax - m_reg <= THR / SCALE), 1)) { mn = m_reg; alpha = 1.f; }
;   else { mn = fmaxf(m_reg, pmax); alpha = __builtin_amdgcn_exp2f((m_reg - mn) * C); m_reg = mn; }
;   float mnC = -mn * C;
;   for (int r = 0; r < 16; ++r) p0[r] = fmaf(p0[r], C, mnC); for (int r = 0; r < 16; ++r) p1[r] = fmaf(p1[r], C, mnC);
;   for (int r = 0; r < 16; ++r) p0[r] = __builtin_amdgcn_exp2f(p0[r]);
; }
; __device__ __forceinline__ void finishSM(f32x16& p0, f32x16& p1, float alpha, float& l_reg, bf16x8& pa0, bf16x8& pa1, bf16x8& pa2, bf16x8& pa3) {
;   for (int r = 0; r < 16; ++r) p1[r] = __builtin_amdgcn_exp2f(p1[r]);
;   float ps = 0; for (int r = 0; r < 16; ++r) ps += p0[r]; for (int r = 0; r < 16; ++r) ps += p1[r];
;   { auto rr = __builtin_amdgcn_permlane32_swap(__float_as_uint(ps), __float_as_uint(ps), false, false);
;     ps = __uint_as_float(rr[0]) + __uint_as_float(rr[1]); }
;   l_reg = l_reg * alpha + ps;
;     ...
;   PK4(p0, 0, pa0); PK4(p0, 8, pa1); PK4(p1, 0, pa2); PK4(p1, 8, pa3);
;     ...
; }
; __device__ __forceinline__ void qkt(f32x16& p0, f32x16& p1, const char* Ks, const bf16x8* qr, int r32, int hi) {
;   p0 = f32x16{}; p1 = f32x16{};
;   for (int d0 = 0; d0 < 8; ++d0) { int cb = (d0 * 16 + hi * 8) * 2;
;     bf16x8 b0 = *reinterpret_cast<const bf16x8*>(Ks + KSWZ(r32, cb));
;     bf16x8 b1 = *reinterpret_cast<const bf16x8*>(Ks + KSWZ(32 + r32, cb));
;     p0 = __builtin_amdgcn_mfma_f32_32x32x16_bf16(b0, qr[d0], p0, 0, 0, 0);
;     p1 = __builtin_amdgcn_mfma_f32_32x32x16_bf16(b1, qr[d0], p1, 0, 0, 0); }
; }
; __device__ __forceinline__ void attn_body(const bf16_t* Qb, const bf16_t* Kh, const bf16_t* Vh, const bf16_t* Gb, bf16_t* Ob, int seq, char* lds,
;                                           const float* qgain, const float* cosA, const float* sinA, int t0) {
;     ...
;     SBAR(); qkt(pA0, pA1, K_lds, qr, r32, hi);
;     finishSM(pB0, pB1, alB, l_reg, pa0, pa1, pa2, pa3); SBAR();
.LBB0_263:
	v_cndmask_b32_e64 v213, v160, v164, s[38:39]
	v_mul_f32_e32 v214, 0xbe0293ee, v213
	v_fmamk_f32 v223, v64, 0x3e0293ee, v214
	v_fmamk_f32 v224, v65, 0x3e0293ee, v214
	v_fmamk_f32 v225, v66, 0x3e0293ee, v214
	v_fmamk_f32 v226, v67, 0x3e0293ee, v214
	v_fmamk_f32 v227, v68, 0x3e0293ee, v214
	v_fmamk_f32 v216, v69, 0x3e0293ee, v214
	v_fmamk_f32 v217, v70, 0x3e0293ee, v214
	v_fmamk_f32 v218, v71, 0x3e0293ee, v214
	ds_read_b128 v[64:67], v201 offset:32768
	ds_read_b128 v[68:71], v201 offset:40960
	ds_read_b128 v[230:233], v204 offset:32768
	ds_read_b128 v[234:237], v204 offset:40960
	ds_read_b128 v[240:243], v205 offset:32768
	ds_read_b128 v[246:249], v205 offset:40960
	v_fmamk_f32 v80, v80, 0x3e0293ee, v214
	v_fmamk_f32 v81, v81, 0x3e0293ee, v214
	v_fmamk_f32 v82, v82, 0x3e0293ee, v214
	v_fmamk_f32 v83, v83, 0x3e0293ee, v214
	v_fmamk_f32 v84, v84, 0x3e0293ee, v214
	v_fmamk_f32 v85, v85, 0x3e0293ee, v214
	v_fmamk_f32 v86, v86, 0x3e0293ee, v214
	v_fmamk_f32 v87, v87, 0x3e0293ee, v214
	v_fmamk_f32 v88, v88, 0x3e0293ee, v214
	v_fmamk_f32 v89, v89, 0x3e0293ee, v214
	v_fmamk_f32 v90, v90, 0x3e0293ee, v214
	v_fmamk_f32 v91, v91, 0x3e0293ee, v214
	v_fmamk_f32 v92, v92, 0x3e0293ee, v214
	v_fmamk_f32 v93, v93, 0x3e0293ee, v214
	v_fmamk_f32 v94, v94, 0x3e0293ee, v214
	v_fmamk_f32 v95, v95, 0x3e0293ee, v214
	v_exp_f32_e32 v160, v80
	v_exp_f32_e32 v175, v81
	v_exp_f32_e32 v161, v82
	v_exp_f32_e32 v174, v83
	v_exp_f32_e32 v162, v84
	v_exp_f32_e32 v173, v85
	v_exp_f32_e32 v163, v86
	v_exp_f32_e32 v172, v87
	v_exp_f32_e32 v164, v88
	v_exp_f32_e32 v171, v89
	v_exp_f32_e32 v165, v90
	v_exp_f32_e32 v170, v91
	v_exp_f32_e32 v166, v92
	v_exp_f32_e32 v169, v93
	v_exp_f32_e32 v167, v94
	v_exp_f32_e32 v168, v95
	v_fmamk_f32 v219, v72, 0x3e0293ee, v214
	v_fmamk_f32 v220, v73, 0x3e0293ee, v214
	v_fmamk_f32 v221, v74, 0x3e0293ee, v214
	v_fmamk_f32 v222, v75, 0x3e0293ee, v214
	v_fmamk_f32 v215, v76, 0x3e0293ee, v214
	v_fmamk_f32 v228, v77, 0x3e0293ee, v214
	v_fmamk_f32 v229, v78, 0x3e0293ee, v214
	v_fmac_f32_e32 v214, 0x3e0293ee, v79
	s_add_i32 s19, s19, 2
	v_exp_f32_e32 v194, v223
	v_exp_f32_e32 v223, v227
	s_waitcnt lgkmcnt(5)
	v_mfma_f32_32x32x16_bf16 v[80:95], v[64:67], v[100:103], 0
	v_exp_f32_e32 v227, v214
	v_add_f32_e32 v214, v175, v160
	v_add_f32_e32 v214, v161, v214
	v_add_f32_e32 v214, v174, v214
	v_add_f32_e32 v214, v162, v214
	v_add_f32_e32 v214, v173, v214
	s_waitcnt lgkmcnt(4)
	v_mfma_f32_32x32x16_bf16 v[64:79], v[68:71], v[100:103], 0
	v_add_f32_e32 v214, v163, v214
	v_add_f32_e32 v214, v172, v214
	v_add_f32_e32 v214, v164, v214
	v_add_f32_e32 v214, v171, v214
	v_add_f32_e32 v214, v165, v214
	v_add_f32_e32 v214, v170, v214
	v_add_f32_e32 v214, v166, v214
	s_waitcnt lgkmcnt(3)
	v_mfma_f32_32x32x16_bf16 v[80:95], v[230:233], v[108:111], v[80:95]
	v_exp_f32_e32 v195, v224
	v_add_f32_e32 v214, v169, v214
	v_exp_f32_e32 v196, v225
	v_add_f32_e32 v214, v167, v214
	v_exp_f32_e32 v197, v226
	v_add_f32_e32 v214, v168, v214
	v_add_f32_e32 v214, v194, v214
	s_waitcnt lgkmcnt(2)
	v_mfma_f32_32x32x16_bf16 v[64:79], v[234:237], v[108:111], v[64:79]
	ds_read_b128 v[230:233], v202 offset:32768
	ds_read_b128 v[234:237], v202 offset:40960
	v_exp_f32_e32 v216, v216
	v_add_f32_e32 v214, v195, v214
	v_exp_f32_e32 v217, v217
	v_add_f32_e32 v214, v196, v214
	v_exp_f32_e32 v218, v218
	v_add_f32_e32 v214, v197, v214
	s_waitcnt lgkmcnt(3)
	v_mfma_f32_32x32x16_bf16 v[80:95], v[240:243], v[96:99], v[80:95]
	v_exp_f32_e32 v219, v219
	v_add_f32_e32 v214, v223, v214
	v_exp_f32_e32 v220, v220
	v_add_f32_e32 v214, v216, v214
	v_exp_f32_e32 v221, v221
	v_add_f32_e32 v214, v217, v214
	v_exp_f32_e32 v222, v222
	s_waitcnt lgkmcnt(2)
	v_mfma_f32_32x32x16_bf16 v[64:79], v[246:249], v[96:99], v[64:79]
	ds_read_b128 v[240:243], v203 offset:32768
	ds_read_b128 v[246:249], v203 offset:40960
	v_add_f32_e32 v214, v218, v214
	v_exp_f32_e32 v224, v215
	v_add_f32_e32 v214, v219, v214
	v_exp_f32_e32 v225, v228
	v_add_f32_e32 v214, v220, v214
	v_exp_f32_e32 v226, v229
	s_waitcnt lgkmcnt(3)
	v_mfma_f32_32x32x16_bf16 v[80:95], v[230:233], v[104:107], v[80:95]
	v_add_f32_e32 v214, v221, v214
	v_add_f32_e32 v214, v222, v214
	v_add_f32_e32 v214, v224, v214
	v_add_f32_e32 v214, v225, v214
	v_add_f32_e32 v214, v226, v214
	v_add_f32_e32 v214, v227, v214
	v_mov_b32_e32 v215, v214
	s_waitcnt lgkmcnt(2)
	v_mfma_f32_32x32x16_bf16 v[64:79], v[234:237], v[104:107], v[64:79]
	ds_read_b128 v[230:233], v206 offset:32768
	ds_read_b128 v[234:237], v206 offset:40960
	v_permlane32_swap_b32_e32 v214, v215
	s_waitcnt lgkmcnt(3)
	v_mfma_f32_32x32x16_bf16 v[80:95], v[240:243], v[116:119], v[80:95]
	s_waitcnt lgkmcnt(2)
	v_mfma_f32_32x32x16_bf16 v[64:79], v[246:249], v[116:119], v[64:79]
	ds_read_b128 v[240:243], v207 offset:32768
	ds_read_b128 v[246:249], v207 offset:40960
	s_waitcnt lgkmcnt(3)
	v_mfma_f32_32x32x16_bf16 v[80:95], v[230:233], v[124:127], v[80:95]
	s_waitcnt lgkmcnt(2)
	v_mfma_f32_32x32x16_bf16 v[64:79], v[234:237], v[124:127], v[64:79]
	ds_read_b128 v[230:233], v208 offset:32768
	ds_read_b128 v[234:237], v208 offset:40960
	s_waitcnt lgkmcnt(3)
	v_mfma_f32_32x32x16_bf16 v[80:95], v[240:243], v[112:115], v[80:95]
	s_waitcnt lgkmcnt(2)
	v_mfma_f32_32x32x16_bf16 v[64:79], v[246:249], v[112:115], v[64:79]
	v_cvt_pk_bf16_f32 v160, v160, v175
	v_cvt_pk_bf16_f32 v161, v161, v174
	v_cvt_pk_bf16_f32 v162, v162, v173
	v_cvt_pk_bf16_f32 v163, v163, v172
	v_cvt_pk_bf16_f32 v164, v164, v171
	v_cvt_pk_bf16_f32 v165, v165, v170
	s_waitcnt lgkmcnt(1)
	v_mfma_f32_32x32x16_bf16 v[80:95], v[230:233], v[120:123], v[80:95]
	v_cvt_pk_bf16_f32 v166, v166, v169
	v_cvt_pk_bf16_f32 v167, v167, v168
	v_cvt_pk_bf16_f32 v168, v194, v195
	v_cvt_pk_bf16_f32 v169, v196, v197
	v_cvt_pk_bf16_f32 v170, v223, v216
	v_cvt_pk_bf16_f32 v171, v217, v218
	v_cvt_pk_bf16_f32 v172, v219, v220
	s_waitcnt lgkmcnt(0)
	v_mfma_f32_32x32x16_bf16 v[64:79], v[234:237], v[120:123], v[64:79]
	v_cvt_pk_bf16_f32 v173, v221, v222
	v_cvt_pk_bf16_f32 v174, v224, v225
	v_cvt_pk_bf16_f32 v175, v226, v227
	v_permlane32_swap_b32_e32 v160, v162
	v_permlane32_swap_b32_e32 v161, v163
	v_permlane32_swap_b32_e32 v164, v166
	v_permlane32_swap_b32_e32 v165, v167
	v_permlane32_swap_b32_e32 v168, v170
	v_permlane32_swap_b32_e32 v169, v171
	v_permlane32_swap_b32_e32 v172, v174
	v_permlane32_swap_b32_e32 v173, v175
	s_cmp_gt_u32 s19, 60
	s_cselect_b64 s[42:43], -1, 0
	s_and_b64 vcc, exec, s[42:43]
	s_cbranch_vccnz .LBB0_265
	s_mov_b32 s20, 0xfffb0000
	s_mov_b32 s21, -1
	v_lshl_add_u64 v[132:133], v[182:183], 0, s[20:21]
	s_mov_b32 s20, 0x50000
	s_mov_b32 s21, 0
	v_lshl_add_u64 v[250:251], v[182:183], 0, s[20:21]
	global_load_dwordx4 v[128:131], v[132:133], off
	global_load_dwordx4 v[136:139], v[250:251], off offset:-1024
	global_load_dwordx4 v[132:135], v[182:183], off
	s_mov_b32 s20, 0xa0000
	v_lshl_add_u64 v[250:251], v[182:183], 0, s[20:21]
	global_load_dwordx4 v[140:143], v[250:251], off offset:-1024

; #define SWRITE(b, i) do { *(bf16x8*)(V_lds + (b) * SHM_V + vst0) = sr_[i].vs0;          \
;     *(bf16x8*)(V_lds + (b) * SHM_V + vst1) = sr_[i].vs1; int kc = sc * 2;               \
;     *(bf16x8*)(K_lds + (b) * SHM_K + KSWZ(sr, kc)) = sr_[i].ks0;                       \
;     *(bf16x8*)(K_lds + (b) * SHM_K + KSWZ(32 + sr, kc)) = sr_[i].ks1; } while (0)
; #define SWAIT() asm volatile("s_waitcnt vmcnt(4)" ::: "memory")
; __device__ __forceinline__ void partialSM(f32x16& p0, f32x16& p1, float& m_reg, float& mn, float& alpha) {
;   constexpr float C = SCALE * 1.4426950408889634f;
;   float pmax = p0[0]; for (int r = 1; r < 16; ++r) pmax = fmaxf(pmax, p0[r]); for (int r = 0; r < 16; ++r) pmax = fmaxf(pmax, p1[r]);
;   { auto rr = __builtin_amdgcn_permlane32_swap(__float_as_uint(pmax), __float_as_uint(pmax), false, false);
;     pmax = fmaxf(__uint_as_float(rr[0]), __uint_as_float(rr[1])); }
;   if (__builtin_expect(__all(pmax - m_reg <= THR / SCALE), 1)) { mn = m_reg; alpha = 1.f; }
;   else { mn = fmaxf(m_reg, pmax); alpha = __builtin_amdgcn_exp2f((m_reg - mn) * C); m_reg = mn; }
;   float mnC = -mn * C;
;   for (int r = 0; r < 16; ++r) p0[r] = fmaf(p0[r], C, mnC); for (int r = 0; r < 16; ++r) p1[r] = fmaf(p1[r], C, mnC);
;   for (int r = 0; r < 16; ++r) p0[r] = __builtin_amdgcn_exp2f(p0[r]);
; }
; __device__ __forceinline__ void finishSM(f32x16& p0, f32x16& p1, float alpha, float& l_reg, bf16x8& pa0, bf16x8& pa1, bf16x8& pa2, bf16x8& pa3) {
;   for (int r = 0; r < 16; ++r) p1[r] = __builtin_amdgcn_exp2f(p1[r]);
;   float ps = 0; for (int r = 0; r < 16; ++r) ps += p0[r]; for (int r = 0; r < 16; ++r) ps += p1[r];
;   { auto rr = __builtin_amdgcn_permlane32_swap(__float_as_uint(ps), __float_as_uint(ps), false, false);
;     ps = __uint_as_float(rr[0]) + __uint_as_float(rr[1]); }
;   l_reg = l_reg * alpha + ps;
; __device__ __forceinline__ void attn_body(const bf16_t* Qb, const bf16_t* Kh, const bf16_t* Vh, const bf16_t* Gb, bf16_t* Ob, int seq, char* lds,
;                                           const float* qgain, const float* cosA, const float* sinA, int t0) {
;     ...
;     pv_d0(o, vb0 + (int)SHM_V, pa0, pa1, pa2, pa3); partialSM(pA0, pA1, m_reg, mnA, alA);
;     __syncthreads(); SWAIT(); SWRITE(1, SO);
;     RESC(alA); __syncthreads();
.LBB0_269:
	v_cndmask_b32_e64 v164, v161, v213, s[38:39]
	v_mul_f32_e32 v150, 0xbe0293ee, v164
	v_mov_b32_e32 v151, v150
	v_pk_fma_f32 v[156:157], v[64:65], s[62:63], v[150:151] op_sel_hi:[1,0,0]
	v_pk_fma_f32 v[154:155], v[66:67], s[62:63], v[150:151] op_sel_hi:[1,0,0]
	v_pk_fma_f32 v[148:149], v[68:69], s[62:63], v[150:151] op_sel_hi:[1,0,0]
	v_pk_fma_f32 v[146:147], v[70:71], s[62:63], v[150:151] op_sel_hi:[1,0,0]
	ds_read_b128 v[64:67], v201 offset:49152
	ds_read_b128 v[68:71], v201 offset:57344
	ds_read_b128 v[218:221], v204 offset:49152
	ds_read_b128 v[222:225], v204 offset:57344
	ds_read_b128 v[240:243], v205 offset:49152
	ds_read_b128 v[246:249], v205 offset:57344
	v_fmamk_f32 v80, v80, 0x3e0293ee, v150
	v_fmamk_f32 v81, v81, 0x3e0293ee, v150
	v_fmamk_f32 v82, v82, 0x3e0293ee, v150
	v_fmamk_f32 v83, v83, 0x3e0293ee, v150
	v_fmamk_f32 v84, v84, 0x3e0293ee, v150
	v_fmamk_f32 v85, v85, 0x3e0293ee, v150
	v_fmamk_f32 v86, v86, 0x3e0293ee, v150
	v_fmamk_f32 v87, v87, 0x3e0293ee, v150
	v_fmamk_f32 v88, v88, 0x3e0293ee, v150
	v_fmamk_f32 v89, v89, 0x3e0293ee, v150
	v_fmamk_f32 v90, v90, 0x3e0293ee, v150
	v_fmamk_f32 v91, v91, 0x3e0293ee, v150
	v_fmamk_f32 v92, v92, 0x3e0293ee, v150
	v_fmamk_f32 v93, v93, 0x3e0293ee, v150
	v_fmamk_f32 v94, v94, 0x3e0293ee, v150
	v_fmac_f32_e32 v151, 0x3e0293ee, v95
	v_exp_f32_e32 v175, v80
	v_exp_f32_e32 v216, v81
	v_exp_f32_e32 v161, v82
	v_exp_f32_e32 v213, v83
	v_exp_f32_e32 v162, v84
	v_exp_f32_e32 v174, v85
	v_exp_f32_e32 v163, v86
	v_exp_f32_e32 v173, v87
	v_exp_f32_e32 v170, v88
	v_exp_f32_e32 v172, v89
	v_exp_f32_e32 v169, v90
	v_exp_f32_e32 v171, v91
	v_exp_f32_e32 v166, v92
	v_exp_f32_e32 v168, v93
	v_exp_f32_e32 v165, v94
	v_exp_f32_e32 v167, v151
	v_add_f32_e32 v239, v210, v211
	v_fmac_f32_e32 v239, v209, v189
	v_add_f32_e32 v189, v214, v215
	s_mov_b64 s[20:21], 0x140000
	v_pk_fma_f32 v[144:145], v[72:73], s[62:63], v[150:151] op_sel_hi:[1,0,0]
	v_pk_fma_f32 v[158:159], v[74:75], s[62:63], v[150:151] op_sel_hi:[1,0,0]
	v_pk_fma_f32 v[152:153], v[76:77], s[62:63], v[150:151] op_sel_hi:[1,0,0]
	v_pk_fma_f32 v[150:151], v[78:79], s[62:63], v[150:151] op_sel_hi:[1,0,0]
	v_fmac_f32_e32 v189, v239, v212
	v_lshl_add_u64 v[182:183], v[182:183], 0, s[20:21]
	s_and_b64 vcc, exec, s[42:43]
	s_cbranch_vccnz .LBB0_271
	v_mov_b32_e32 v209, v160
	s_branch .LBB0_259
